# f32 weight sources of the remaining conversion loops (beside top-k, merge and out weights) read with non-temporal loads
# speedup vs baseline: 1.0060x; 1.0060x over previous
; #define LAS __attribute__((address_space(3)))
;     ...
;         for (int q = 0; q < 4; ++q) { const int it = gi * 4 + q;
;             v[q][0] = (f32x4){0.f, 0.f, 0.f, 0.f}; v[q][1] = (f32x4){0.f, 0.f, 0.f, 0.f};
;             if (it < total) { const int b = it / per, r = it % per, k0 = (r / tn) * 64, n0 = (r % tn) * 64;
;                 const float* sp = src + (size_t)b * sbs + (size_t)k0 * N + n0; const int c4 = (tid & 15) * 4;
;                 if (n0 + c4 < N) { v[q][0] = *(const f32x4*)(sp + (size_t)(tid >> 4) * N + c4); v[q][1] = *(const f32x4*)(sp + (size_t)((tid >> 4) + 32) * N + c4); } } }
; __device__ void phase_topk(const Params& p, int l, LAS unsigned char* lds) {
;     ...
;         if (l == 1 && gridDim.x > NE) cvt_job((LAS float*)lds, p.ewg + (size_t)NE * FF * 1024, (bf16_t*)(p.ws + WS_WG) + (size_t)NE * FF * 1024, NE, 1024, FF, 1024, 0, (size_t)1024 * FF, (size_t)FF * 1024, (int)blockIdx.x - NE, (int)gridDim.x - NE);
.LBB0_247:
	s_ashr_i32 s4, s16, 31
	s_lshr_b32 s4, s4, 23
	s_add_i32 s4, s16, s4
	s_and_b32 s4, s4, 0xfffffe00
	s_sub_i32 s4, s16, s4
	s_sext_i32_i16 s5, s4
	s_bfe_u32 s5, s5, 0x5001a
	s_add_i32 s20, s4, s5
	s_and_b32 s5, s20, 0xffe0
	s_sub_i32 s4, s4, s5
	s_sext_i32_i16 s4, s4
	s_lshl_b32 s8, s4, 6
	v_or_b32_e32 v0, s8, v32
	s_movk_i32 s4, 0x800
	v_cmp_gt_i32_e32 vcc, s4, v0
	v_mov_b32_e32 v8, 0
	v_mov_b32_e32 v0, 0
	v_mov_b32_e32 v1, 0
	v_mov_b32_e32 v2, 0
	v_mov_b32_e32 v3, 0
	v_mov_b32_e32 v4, 0
	v_mov_b32_e32 v5, 0
	v_mov_b32_e32 v6, 0
	v_mov_b32_e32 v7, 0
	s_and_saveexec_b64 s[4:5], vcc
	s_cbranch_execz .LBB0_249
	s_ashr_i32 s6, s17, 31
	s_lshr_b32 s6, s6, 25
	s_add_i32 s6, s17, s6
	s_ashr_i32 s6, s6, 7
	s_ashr_i32 s7, s6, 31
	s_lshl_b64 s[6:7], s[6:7], 23
	s_add_u32 s9, s85, s6
	v_readlane_b32 s6, v252, 56
	s_addc_u32 s10, s6, s7
	s_sext_i32_i16 s6, s20
	s_lshl_b32 s6, s6, 1
	s_andn2_b32 s6, s6, 63
	s_ashr_i32 s7, s6, 31
	s_lshl_b64 s[6:7], s[6:7], 13
	s_add_u32 s11, s9, s6
	s_addc_u32 s10, s10, s7
	s_ashr_i32 s9, s8, 31
	s_lshl_b64 s[6:7], s[8:9], 2
	s_add_u32 s6, s11, s6
	s_addc_u32 s7, s10, s7
	v_lshl_add_u64 v[0:1], v[34:35], 2, s[6:7]
	v_lshlrev_b32_e32 v188, 2, v32
	v_lshl_add_u64 v[2:3], v[36:37], 2, s[6:7]
	v_lshl_add_u64 v[0:1], v[0:1], 0, v[188:189]
	v_lshl_add_u64 v[2:3], v[2:3], 0, v[188:189]
	global_load_dwordx4 v[4:7], v[0:1], off nt
	s_nop 0
	global_load_dwordx4 v[0:3], v[2:3], off nt
.LBB0_249:
	s_or_b64 exec, exec, s[4:5]
	s_add_i32 s18, s16, 1
	s_cmpk_lt_i32 s18, 0x2000
	s_cselect_b64 s[4:5], -1, 0
	s_cmpk_gt_i32 s18, 0x1fff
	v_mov_b32_e32 v9, 0
	v_mov_b32_e32 v10, 0
	v_mov_b32_e32 v11, 0
	v_mov_b32_e32 v12, 0
	v_mov_b32_e32 v13, 0
	v_mov_b32_e32 v14, 0
	v_mov_b32_e32 v15, 0
	s_cbranch_scc1 .LBB0_253
	s_ashr_i32 s6, s18, 31
	s_lshr_b32 s6, s6, 23
	s_add_i32 s9, s18, s6
	s_and_b32 s6, s9, 0xfe00
	s_sub_i32 s6, s18, s6
	s_sext_i32_i16 s7, s6
	s_bfe_u32 s7, s7, 0x5001a
	s_add_i32 s11, s6, s7
	s_and_b32 s7, s11, 0xffe0
	s_sub_i32 s6, s6, s7
	s_sext_i32_i16 s6, s6
	s_lshl_b32 s10, s6, 6
	v_or_b32_e32 v8, s10, v32
	s_movk_i32 s6, 0x800
	v_cmp_gt_i32_e32 vcc, s6, v8
	v_mov_b32_e32 v15, 0
	v_mov_b32_e32 v14, 0
	v_mov_b32_e32 v13, 0
	v_mov_b32_e32 v12, 0
	v_mov_b32_e32 v11, 0
	v_mov_b32_e32 v10, 0
	v_mov_b32_e32 v9, 0
	v_mov_b32_e32 v8, 0
	s_and_saveexec_b64 s[6:7], vcc
	s_cbranch_execz .LBB0_252
	s_ashr_i32 s12, s9, 9
	s_sext_i32_i16 s11, s11
	s_ashr_i32 s13, s12, 31
	s_lshr_b32 s11, s11, 5
	s_lshl_b64 s[12:13], s[12:13], 23
	s_add_u32 s9, s85, s12
	v_readlane_b32 s12, v252, 56
	s_sext_i32_i16 s11, s11
	s_addc_u32 s14, s12, s13
	s_lshl_b32 s12, s11, 6
	s_ashr_i32 s13, s12, 31
	s_lshl_b64 s[12:13], s[12:13], 13
	s_add_u32 s9, s9, s12
	s_addc_u32 s12, s14, s13
	s_ashr_i32 s11, s10, 31
	s_lshl_b64 s[10:11], s[10:11], 2
	s_add_u32 s10, s9, s10
	s_addc_u32 s11, s12, s11
	v_lshl_add_u64 v[8:9], v[34:35], 2, s[10:11]
	v_lshlrev_b32_e32 v188, 2, v32
	v_lshl_add_u64 v[10:11], v[36:37], 2, s[10:11]
	v_lshl_add_u64 v[8:9], v[8:9], 0, v[188:189]
	v_lshl_add_u64 v[10:11], v[10:11], 0, v[188:189]
	global_load_dwordx4 v[12:15], v[8:9], off nt
	s_nop 0
	global_load_dwordx4 v[8:11], v[10:11], off nt

; #define LAS __attribute__((address_space(3)))
;     ...
;         for (int q = 0; q < 4; ++q) { const int it = gi * 4 + q;
;             v[q][0] = (f32x4){0.f, 0.f, 0.f, 0.f}; v[q][1] = (f32x4){0.f, 0.f, 0.f, 0.f};
;             if (it < total) { const int b = it / per, r = it % per, k0 = (r / tn) * 64, n0 = (r % tn) * 64;
;                 const float* sp = src + (size_t)b * sbs + (size_t)k0 * N + n0; const int c4 = (tid & 15) * 4;
;                 if (n0 + c4 < N) { v[q][0] = *(const f32x4*)(sp + (size_t)(tid >> 4) * N + c4); v[q][1] = *(const f32x4*)(sp + (size_t)((tid >> 4) + 32) * N + c4); } } }
; __device__ void phase_topk(const Params& p, int l, LAS unsigned char* lds) {
;     ...
;         if (l == 1 && gridDim.x > NE) cvt_job((LAS float*)lds, p.ewg + (size_t)NE * FF * 1024, (bf16_t*)(p.ws + WS_WG) + (size_t)NE * FF * 1024, NE, 1024, FF, 1024, 0, (size_t)1024 * FF, (size_t)FF * 1024, (int)blockIdx.x - NE, (int)gridDim.x - NE);
.LBB0_253:
	s_add_i32 s19, s16, 2
	s_cmpk_lt_i32 s19, 0x2000
	v_mov_b32_e32 v16, 0
	s_cselect_b64 s[6:7], -1, 0
	s_cmpk_gt_i32 s19, 0x1fff
	v_mov_b32_e32 v20, 0
	v_mov_b32_e32 v21, 0
	v_mov_b32_e32 v22, 0
	v_mov_b32_e32 v23, 0
	v_mov_b32_e32 v24, 0
	v_mov_b32_e32 v25, 0
	v_mov_b32_e32 v26, 0
	v_mov_b32_e32 v27, 0
	s_cbranch_scc1 .LBB0_257
	s_ashr_i32 s9, s19, 31
	s_lshr_b32 s9, s9, 23
	s_add_i32 s9, s19, s9
	s_and_b32 s10, s9, 0xfe00
	s_sub_i32 s10, s19, s10
	s_sext_i32_i16 s11, s10
	s_bfe_u32 s11, s11, 0x5001a
	s_add_i32 s13, s10, s11
	s_and_b32 s11, s13, 0xffe0
	s_sub_i32 s10, s10, s11
	s_sext_i32_i16 s10, s10
	s_lshl_b32 s12, s10, 6
	v_or_b32_e32 v17, s12, v32
	s_movk_i32 s10, 0x800
	v_cmp_gt_i32_e32 vcc, s10, v17
	v_mov_b32_e32 v27, 0
	v_mov_b32_e32 v26, 0
	v_mov_b32_e32 v25, 0
	v_mov_b32_e32 v24, 0
	v_mov_b32_e32 v23, 0
	v_mov_b32_e32 v22, 0
	v_mov_b32_e32 v21, 0
	v_mov_b32_e32 v20, 0
	s_and_saveexec_b64 s[10:11], vcc
	s_cbranch_execz .LBB0_256
	s_ashr_i32 s14, s9, 9
	s_sext_i32_i16 s13, s13
	s_ashr_i32 s15, s14, 31
	s_lshr_b32 s13, s13, 5
	s_lshl_b64 s[14:15], s[14:15], 23
	s_add_u32 s9, s85, s14
	v_readlane_b32 s14, v252, 56
	s_sext_i32_i16 s13, s13
	s_addc_u32 s21, s14, s15
	s_lshl_b32 s14, s13, 6
	s_ashr_i32 s15, s14, 31
	s_lshl_b64 s[14:15], s[14:15], 13
	s_add_u32 s9, s9, s14
	s_addc_u32 s14, s21, s15
	s_ashr_i32 s13, s12, 31
	s_lshl_b64 s[12:13], s[12:13], 2
	s_add_u32 s12, s9, s12
	s_addc_u32 s13, s14, s13
	v_lshl_add_u64 v[18:19], v[34:35], 2, s[12:13]
	v_lshlrev_b32_e32 v188, 2, v32
	v_lshl_add_u64 v[20:21], v[36:37], 2, s[12:13]
	v_lshl_add_u64 v[18:19], v[18:19], 0, v[188:189]
	v_lshl_add_u64 v[20:21], v[20:21], 0, v[188:189]
	global_load_dwordx4 v[24:27], v[18:19], off nt
	s_nop 0
	global_load_dwordx4 v[20:23], v[20:21], off nt

; #define LAS __attribute__((address_space(3)))
;     ...
;         for (int q = 0; q < 4; ++q) { const int it = gi * 4 + q;
;             v[q][0] = (f32x4){0.f, 0.f, 0.f, 0.f}; v[q][1] = (f32x4){0.f, 0.f, 0.f, 0.f};
;             if (it < total) { const int b = it / per, r = it % per, k0 = (r / tn) * 64, n0 = (r % tn) * 64;
;                 const float* sp = src + (size_t)b * sbs + (size_t)k0 * N + n0; const int c4 = (tid & 15) * 4;
;                 if (n0 + c4 < N) { v[q][0] = *(const f32x4*)(sp + (size_t)(tid >> 4) * N + c4); v[q][1] = *(const f32x4*)(sp + (size_t)((tid >> 4) + 32) * N + c4); } } }
; __device__ void phase_topk(const Params& p, int l, LAS unsigned char* lds) {
;     ...
;         if (l == 1 && gridDim.x > NE) cvt_job((LAS float*)lds, p.ewg + (size_t)NE * FF * 1024, (bf16_t*)(p.ws + WS_WG) + (size_t)NE * FF * 1024, NE, 1024, FF, 1024, 0, (size_t)1024 * FF, (size_t)FF * 1024, (int)blockIdx.x - NE, (int)gridDim.x - NE);
.LBB0_257:
	s_add_i32 s21, s16, 3
	s_cmpk_lt_i32 s21, 0x2000
	s_cselect_b64 s[10:11], -1, 0
	s_cmpk_gt_i32 s21, 0x1fff
	v_mov_b32_e32 v17, 0
	v_mov_b32_e32 v18, 0
	v_mov_b32_e32 v19, 0
	v_mov_b32_e32 v28, 0
	v_mov_b32_e32 v29, 0
	v_mov_b32_e32 v30, 0
	v_mov_b32_e32 v31, 0
	s_cbranch_scc1 .LBB0_261
	s_ashr_i32 s9, s21, 31
	s_lshr_b32 s9, s9, 23
	s_add_i32 s9, s21, s9
	s_and_b32 s12, s9, 0xfe00
	s_sub_i32 s12, s21, s12
	s_sext_i32_i16 s13, s12
	s_bfe_u32 s13, s13, 0x5001a
	s_add_i32 s15, s12, s13
	s_and_b32 s13, s15, 0xffe0
	s_sub_i32 s12, s12, s13
	s_sext_i32_i16 s12, s12
	s_lshl_b32 s14, s12, 6
	v_or_b32_e32 v16, s14, v32
	s_movk_i32 s12, 0x800
	v_cmp_gt_i32_e32 vcc, s12, v16
	v_mov_b32_e32 v31, 0
	v_mov_b32_e32 v30, 0
	v_mov_b32_e32 v29, 0
	v_mov_b32_e32 v28, 0
	v_mov_b32_e32 v19, 0
	v_mov_b32_e32 v18, 0
	v_mov_b32_e32 v17, 0
	v_mov_b32_e32 v16, 0
	s_and_saveexec_b64 s[12:13], vcc
	s_cbranch_execz .LBB0_260
	s_ashr_i32 s22, s9, 9
	s_sext_i32_i16 s15, s15
	s_ashr_i32 s23, s22, 31
	s_lshr_b32 s15, s15, 5
	s_lshl_b64 s[22:23], s[22:23], 23
	s_add_u32 s9, s85, s22
	v_readlane_b32 s22, v252, 56
	s_sext_i32_i16 s15, s15
	s_addc_u32 s24, s22, s23
	s_lshl_b32 s22, s15, 6
	s_ashr_i32 s23, s22, 31
	s_lshl_b64 s[22:23], s[22:23], 13
	s_add_u32 s9, s9, s22
	s_addc_u32 s22, s24, s23
	s_ashr_i32 s15, s14, 31
	s_lshl_b64 s[14:15], s[14:15], 2
	s_add_u32 s14, s9, s14
	s_addc_u32 s15, s22, s15
	v_lshl_add_u64 v[16:17], v[34:35], 2, s[14:15]
	v_lshlrev_b32_e32 v188, 2, v32
	v_lshl_add_u64 v[18:19], v[36:37], 2, s[14:15]
	v_lshl_add_u64 v[16:17], v[16:17], 0, v[188:189]
	v_lshl_add_u64 v[18:19], v[18:19], 0, v[188:189]
	global_load_dwordx4 v[28:31], v[16:17], off nt
	s_nop 0
	global_load_dwordx4 v[16:19], v[18:19], off nt

; #define LAS __attribute__((address_space(3)))
;     ...
;         for (int q = 0; q < 4; ++q) { const int it = gi * 4 + q;
;             v[q][0] = (f32x4){0.f, 0.f, 0.f, 0.f}; v[q][1] = (f32x4){0.f, 0.f, 0.f, 0.f};
;             if (it < total) { const int b = it / per, r = it % per, k0 = (r / tn) * 64, n0 = (r % tn) * 64;
;                 const float* sp = src + (size_t)b * sbs + (size_t)k0 * N + n0; const int c4 = (tid & 15) * 4;
;                 if (n0 + c4 < N) { v[q][0] = *(const f32x4*)(sp + (size_t)(tid >> 4) * N + c4); v[q][1] = *(const f32x4*)(sp + (size_t)((tid >> 4) + 32) * N + c4); } } }
; __device__ void phase_topk(const Params& p, int l, LAS unsigned char* lds) {
;     ...
;         if (l == 0 && gridDim.x > NE) cvt_job((LAS float*)lds, p.ewd + (size_t)NE * FF * 1024, (bf16_t*)(p.ws + WS_WD) + (size_t)NE * FF * 1024, NE, FF, 1024, FF, 0, (size_t)FF * 1024, (size_t)1024 * FF, (int)blockIdx.x - NE, (int)gridDim.x - NE);
.LBB0_282:
	s_ashr_i32 s4, s16, 31
	s_lshr_b32 s4, s4, 23
	s_add_i32 s4, s16, s4
	s_and_b32 s4, s4, 0xfffffe00
	s_sub_i32 s4, s16, s4
	s_sext_i32_i16 s5, s4
	s_bfe_u32 s5, s5, 0x4001b
	s_add_i32 s20, s4, s5
	s_and_b32 s5, s20, 0xfff0
	s_sub_i32 s4, s4, s5
	s_sext_i32_i16 s4, s4
	s_lshl_b32 s8, s4, 6
	v_or_b32_e32 v0, s8, v32
	v_cmp_gt_i32_e32 vcc, s93, v0
	v_mov_b32_e32 v8, 0
	v_mov_b32_e32 v0, 0
	v_mov_b32_e32 v1, 0
	v_mov_b32_e32 v2, 0
	v_mov_b32_e32 v3, 0
	v_mov_b32_e32 v4, 0
	v_mov_b32_e32 v5, 0
	v_mov_b32_e32 v6, 0
	v_mov_b32_e32 v7, 0
	s_and_saveexec_b64 s[4:5], vcc
	s_cbranch_execz .LBB0_284
	s_ashr_i32 s6, s17, 31
	s_lshr_b32 s6, s6, 25
	s_add_i32 s6, s17, s6
	s_ashr_i32 s6, s6, 7
	s_ashr_i32 s7, s6, 31
	s_lshl_b64 s[6:7], s[6:7], 23
	v_readlane_b32 s9, v252, 32
	s_add_u32 s9, s9, s6
	v_readlane_b32 s6, v252, 33
	s_addc_u32 s10, s6, s7
	s_sext_i32_i16 s6, s20
	s_lshl_b32 s6, s6, 2
	s_andn2_b32 s6, s6, 63
	s_ashr_i32 s7, s6, 31
	s_lshl_b64 s[6:7], s[6:7], 12
	s_add_u32 s11, s9, s6
	s_addc_u32 s10, s10, s7
	s_ashr_i32 s9, s8, 31
	s_lshl_b64 s[6:7], s[8:9], 2
	s_add_u32 s6, s11, s6
	s_addc_u32 s7, s10, s7
	v_lshl_add_u64 v[0:1], v[34:35], 2, s[6:7]
	v_lshlrev_b32_e32 v188, 2, v32
	v_lshl_add_u64 v[2:3], v[36:37], 2, s[6:7]
	v_lshl_add_u64 v[0:1], v[0:1], 0, v[188:189]
	v_lshl_add_u64 v[2:3], v[2:3], 0, v[188:189]
	global_load_dwordx4 v[4:7], v[0:1], off nt
	s_nop 0
	global_load_dwordx4 v[0:3], v[2:3], off nt
.LBB0_284:
	s_or_b64 exec, exec, s[4:5]
	s_add_i32 s18, s16, 1
	s_cmpk_lt_i32 s18, 0x2000
	s_cselect_b64 s[4:5], -1, 0
	s_cmpk_gt_i32 s18, 0x1fff
	v_mov_b32_e32 v9, 0
	v_mov_b32_e32 v10, 0
	v_mov_b32_e32 v11, 0
	v_mov_b32_e32 v12, 0
	v_mov_b32_e32 v13, 0
	v_mov_b32_e32 v14, 0
	v_mov_b32_e32 v15, 0
	s_cbranch_scc1 .LBB0_288
	s_ashr_i32 s6, s18, 31
	s_lshr_b32 s6, s6, 23
	s_add_i32 s9, s18, s6
	s_and_b32 s6, s9, 0xfe00
	s_sub_i32 s6, s18, s6
	s_sext_i32_i16 s7, s6
	s_bfe_u32 s7, s7, 0x4001b
	s_add_i32 s11, s6, s7
	s_and_b32 s7, s11, 0xfff0
	s_sub_i32 s6, s6, s7
	s_sext_i32_i16 s6, s6
	s_lshl_b32 s10, s6, 6
	v_or_b32_e32 v8, s10, v32
	v_cmp_gt_i32_e32 vcc, s93, v8
	v_mov_b32_e32 v15, 0
	v_mov_b32_e32 v14, 0
	v_mov_b32_e32 v13, 0
	v_mov_b32_e32 v12, 0
	v_mov_b32_e32 v11, 0
	v_mov_b32_e32 v10, 0
	v_mov_b32_e32 v9, 0
	v_mov_b32_e32 v8, 0
	s_and_saveexec_b64 s[6:7], vcc
	s_cbranch_execz .LBB0_287
	s_ashr_i32 s12, s9, 9
	s_sext_i32_i16 s11, s11
	s_ashr_i32 s13, s12, 31
	s_lshr_b32 s11, s11, 4
	s_lshl_b64 s[12:13], s[12:13], 23
	v_readlane_b32 s9, v252, 32
	s_add_u32 s9, s9, s12
	v_readlane_b32 s12, v252, 33
	s_sext_i32_i16 s11, s11
	s_addc_u32 s14, s12, s13
	s_lshl_b32 s12, s11, 6
	s_ashr_i32 s13, s12, 31
	s_lshl_b64 s[12:13], s[12:13], 12
	s_add_u32 s9, s9, s12
	s_addc_u32 s12, s14, s13
	s_ashr_i32 s11, s10, 31
	s_lshl_b64 s[10:11], s[10:11], 2
	s_add_u32 s10, s9, s10
	s_addc_u32 s11, s12, s11
	v_lshl_add_u64 v[8:9], v[34:35], 2, s[10:11]
	v_lshlrev_b32_e32 v188, 2, v32
	v_lshl_add_u64 v[10:11], v[36:37], 2, s[10:11]
	v_lshl_add_u64 v[8:9], v[8:9], 0, v[188:189]
	v_lshl_add_u64 v[10:11], v[10:11], 0, v[188:189]
	global_load_dwordx4 v[12:15], v[8:9], off nt
	s_nop 0
	global_load_dwordx4 v[8:11], v[10:11], off nt

; #define LAS __attribute__((address_space(3)))
;     ...
;         for (int q = 0; q < 4; ++q) { const int it = gi * 4 + q;
;             v[q][0] = (f32x4){0.f, 0.f, 0.f, 0.f}; v[q][1] = (f32x4){0.f, 0.f, 0.f, 0.f};
;             if (it < total) { const int b = it / per, r = it % per, k0 = (r / tn) * 64, n0 = (r % tn) * 64;
;                 const float* sp = src + (size_t)b * sbs + (size_t)k0 * N + n0; const int c4 = (tid & 15) * 4;
;                 if (n0 + c4 < N) { v[q][0] = *(const f32x4*)(sp + (size_t)(tid >> 4) * N + c4); v[q][1] = *(const f32x4*)(sp + (size_t)((tid >> 4) + 32) * N + c4); } } }
; __device__ void phase_topk(const Params& p, int l, LAS unsigned char* lds) {
;     ...
;         if (l == 0 && gridDim.x > NE) cvt_job((LAS float*)lds, p.ewd + (size_t)NE * FF * 1024, (bf16_t*)(p.ws + WS_WD) + (size_t)NE * FF * 1024, NE, FF, 1024, FF, 0, (size_t)FF * 1024, (size_t)1024 * FF, (int)blockIdx.x - NE, (int)gridDim.x - NE);
.LBB0_288:
	s_add_i32 s19, s16, 2
	s_cmpk_lt_i32 s19, 0x2000
	v_mov_b32_e32 v16, 0
	s_cselect_b64 s[6:7], -1, 0
	s_cmpk_gt_i32 s19, 0x1fff
	v_mov_b32_e32 v20, 0
	v_mov_b32_e32 v21, 0
	v_mov_b32_e32 v22, 0
	v_mov_b32_e32 v23, 0
	v_mov_b32_e32 v24, 0
	v_mov_b32_e32 v25, 0
	v_mov_b32_e32 v26, 0
	v_mov_b32_e32 v27, 0
	s_cbranch_scc1 .LBB0_292
	s_ashr_i32 s9, s19, 31
	s_lshr_b32 s9, s9, 23
	s_add_i32 s9, s19, s9
	s_and_b32 s10, s9, 0xfe00
	s_sub_i32 s10, s19, s10
	s_sext_i32_i16 s11, s10
	s_bfe_u32 s11, s11, 0x4001b
	s_add_i32 s13, s10, s11
	s_and_b32 s11, s13, 0xfff0
	s_sub_i32 s10, s10, s11
	s_sext_i32_i16 s10, s10
	s_lshl_b32 s12, s10, 6
	v_or_b32_e32 v17, s12, v32
	v_cmp_gt_i32_e32 vcc, s93, v17
	v_mov_b32_e32 v27, 0
	v_mov_b32_e32 v26, 0
	v_mov_b32_e32 v25, 0
	v_mov_b32_e32 v24, 0
	v_mov_b32_e32 v23, 0
	v_mov_b32_e32 v22, 0
	v_mov_b32_e32 v21, 0
	v_mov_b32_e32 v20, 0
	s_and_saveexec_b64 s[10:11], vcc
	s_cbranch_execz .LBB0_291
	s_ashr_i32 s14, s9, 9
	s_sext_i32_i16 s13, s13
	s_ashr_i32 s15, s14, 31
	s_lshr_b32 s13, s13, 4
	s_lshl_b64 s[14:15], s[14:15], 23
	v_readlane_b32 s9, v252, 32
	s_add_u32 s9, s9, s14
	v_readlane_b32 s14, v252, 33
	s_sext_i32_i16 s13, s13
	s_addc_u32 s21, s14, s15
	s_lshl_b32 s14, s13, 6
	s_ashr_i32 s15, s14, 31
	s_lshl_b64 s[14:15], s[14:15], 12
	s_add_u32 s9, s9, s14
	s_addc_u32 s14, s21, s15
	s_ashr_i32 s13, s12, 31
	s_lshl_b64 s[12:13], s[12:13], 2
	s_add_u32 s12, s9, s12
	s_addc_u32 s13, s14, s13
	v_lshl_add_u64 v[18:19], v[34:35], 2, s[12:13]
	v_lshlrev_b32_e32 v188, 2, v32
	v_lshl_add_u64 v[20:21], v[36:37], 2, s[12:13]
	v_lshl_add_u64 v[18:19], v[18:19], 0, v[188:189]
	v_lshl_add_u64 v[20:21], v[20:21], 0, v[188:189]
	global_load_dwordx4 v[24:27], v[18:19], off nt
	s_nop 0
	global_load_dwordx4 v[20:23], v[20:21], off nt

; #define LAS __attribute__((address_space(3)))
;     ...
;         for (int q = 0; q < 4; ++q) { const int it = gi * 4 + q;
;             v[q][0] = (f32x4){0.f, 0.f, 0.f, 0.f}; v[q][1] = (f32x4){0.f, 0.f, 0.f, 0.f};
;             if (it < total) { const int b = it / per, r = it % per, k0 = (r / tn) * 64, n0 = (r % tn) * 64;
;                 const float* sp = src + (size_t)b * sbs + (size_t)k0 * N + n0; const int c4 = (tid & 15) * 4;
;                 if (n0 + c4 < N) { v[q][0] = *(const f32x4*)(sp + (size_t)(tid >> 4) * N + c4); v[q][1] = *(const f32x4*)(sp + (size_t)((tid >> 4) + 32) * N + c4); } } }
; __device__ void phase_topk(const Params& p, int l, LAS unsigned char* lds) {
;     ...
;         if (l == 0 && gridDim.x > NE) cvt_job((LAS float*)lds, p.ewd + (size_t)NE * FF * 1024, (bf16_t*)(p.ws + WS_WD) + (size_t)NE * FF * 1024, NE, FF, 1024, FF, 0, (size_t)FF * 1024, (size_t)1024 * FF, (int)blockIdx.x - NE, (int)gridDim.x - NE);
.LBB0_292:
	s_add_i32 s21, s16, 3
	s_cmpk_lt_i32 s21, 0x2000
	s_cselect_b64 s[10:11], -1, 0
	s_cmpk_gt_i32 s21, 0x1fff
	v_mov_b32_e32 v17, 0
	v_mov_b32_e32 v18, 0
	v_mov_b32_e32 v19, 0
	v_mov_b32_e32 v28, 0
	v_mov_b32_e32 v29, 0
	v_mov_b32_e32 v30, 0
	v_mov_b32_e32 v31, 0
	s_cbranch_scc1 .LBB0_296
	s_ashr_i32 s9, s21, 31
	s_lshr_b32 s9, s9, 23
	s_add_i32 s9, s21, s9
	s_and_b32 s12, s9, 0xfe00
	s_sub_i32 s12, s21, s12
	s_sext_i32_i16 s13, s12
	s_bfe_u32 s13, s13, 0x4001b
	s_add_i32 s15, s12, s13
	s_and_b32 s13, s15, 0xfff0
	s_sub_i32 s12, s12, s13
	s_sext_i32_i16 s12, s12
	s_lshl_b32 s14, s12, 6
	v_or_b32_e32 v16, s14, v32
	v_cmp_gt_i32_e32 vcc, s93, v16
	v_mov_b32_e32 v31, 0
	v_mov_b32_e32 v30, 0
	v_mov_b32_e32 v29, 0
	v_mov_b32_e32 v28, 0
	v_mov_b32_e32 v19, 0
	v_mov_b32_e32 v18, 0
	v_mov_b32_e32 v17, 0
	v_mov_b32_e32 v16, 0
	s_and_saveexec_b64 s[12:13], vcc
	s_cbranch_execz .LBB0_295
	s_ashr_i32 s22, s9, 9
	s_sext_i32_i16 s15, s15
	s_ashr_i32 s23, s22, 31
	s_lshr_b32 s15, s15, 4
	s_lshl_b64 s[22:23], s[22:23], 23
	v_readlane_b32 s9, v252, 32
	s_add_u32 s9, s9, s22
	v_readlane_b32 s22, v252, 33
	s_sext_i32_i16 s15, s15
	s_addc_u32 s24, s22, s23
	s_lshl_b32 s22, s15, 6
	s_ashr_i32 s23, s22, 31
	s_lshl_b64 s[22:23], s[22:23], 12
	s_add_u32 s9, s9, s22
	s_addc_u32 s22, s24, s23
	s_ashr_i32 s15, s14, 31
	s_lshl_b64 s[14:15], s[14:15], 2
	s_add_u32 s14, s9, s14
	s_addc_u32 s15, s22, s15
	v_lshl_add_u64 v[16:17], v[34:35], 2, s[14:15]
	v_lshlrev_b32_e32 v188, 2, v32
	v_lshl_add_u64 v[18:19], v[36:37], 2, s[14:15]
	v_lshl_add_u64 v[16:17], v[16:17], 0, v[188:189]
	v_lshl_add_u64 v[18:19], v[18:19], 0, v[188:189]
	global_load_dwordx4 v[28:31], v[16:17], off nt
	s_nop 0
	global_load_dwordx4 v[16:19], v[18:19], off nt

;     ...
;         for (int q = 0; q < 4; ++q) { const int it = gi * 4 + q;
;             v[q][0] = (f32x4){0.f, 0.f, 0.f, 0.f}; v[q][1] = (f32x4){0.f, 0.f, 0.f, 0.f};
;             if (it < total) { const int b = it / per, r = it % per, k0 = (r / tn) * 64, n0 = (r % tn) * 64;
;                 const float* sp = src + (size_t)b * sbs + (size_t)k0 * N + n0; const int c4 = (tid & 15) * 4;
;                 if (n0 + c4 < N) { v[q][0] = *(const f32x4*)(sp + (size_t)(tid >> 4) * N + c4); v[q][1] = *(const f32x4*)(sp + (size_t)((tid >> 4) + 32) * N + c4); } } }
; __device__ void phase_convert(const Params& p, LAS unsigned char* lds) {
;     ...
;     cvt_job(tile, p.wba, (bf16_t*)(ws + WS_WMRG), NL, 512, 1024, 512, 0, (size_t)512 * 1024, (size_t)3 * 1024 * 512, (int)((blockIdx.x + gridDim.x - 104 % gridDim.x) % gridDim.x), (int)gridDim.x);
;     cvt_job(tile, p.wbc, (bf16_t*)(ws + WS_WMRG) + (size_t)1024 * 512, NL, 512, 1024, 512, 0, (size_t)512 * 1024, (size_t)3 * 1024 * 512, (int)((blockIdx.x + gridDim.x - 168 % gridDim.x) % gridDim.x), (int)gridDim.x);
;     cvt_job(tile, p.wbg, (bf16_t*)(ws + WS_WMRG) + (size_t)2 * 1024 * 512, NL, 512, 1024, 512, 0, (size_t)512 * 1024, (size_t)3 * 1024 * 512, (int)((blockIdx.x + gridDim.x - 232 % gridDim.x) % gridDim.x), (int)gridDim.x);
.LBB0_547:
	s_ashr_i32 s4, s16, 31
	s_lshr_b32 s4, s4, 25
	s_add_i32 s4, s16, s4
	s_and_b32 s4, s4, 0xff80
	s_sub_i32 s4, s16, s4
	s_bfe_i32 s5, s4, 0x80000
	s_bfe_u32 s5, s5, 0x4000b
	s_add_i32 s18, s4, s5
	s_and_b32 s5, s18, 0xf0
	s_sub_i32 s4, s4, s5
	s_sext_i32_i8 s4, s4
	s_lshl_b32 s4, s4, 6
	v_or_b32_e32 v0, s4, v32
	v_cmp_gt_i32_e32 vcc, s93, v0
	v_mov_b32_e32 v8, 0
	v_mov_b32_e32 v0, 0
	v_mov_b32_e32 v1, 0
	v_mov_b32_e32 v2, 0
	v_mov_b32_e32 v3, 0
	v_mov_b32_e32 v4, 0
	v_mov_b32_e32 v5, 0
	v_mov_b32_e32 v6, 0
	v_mov_b32_e32 v7, 0
	s_and_saveexec_b64 s[6:7], vcc
	s_cbranch_execz .LBB0_549
	s_ashr_i32 s5, s17, 31
	s_lshr_b32 s5, s5, 27
	s_add_i32 s5, s17, s5
	s_ashr_i32 s8, s5, 5
	s_ashr_i32 s9, s8, 31
	v_readlane_b32 s40, v254, 48
	s_lshl_b64 s[8:9], s[8:9], 21
	v_readlane_b32 s54, v254, 62
	v_readlane_b32 s55, v254, 63
	s_add_u32 s5, s54, s8
	s_addc_u32 s10, s55, s9
	s_bfe_i32 s8, s18, 0x80000
	s_sext_i32_i16 s8, s8
	s_lshl_b32 s8, s8, 2
	s_andn2_b32 s8, s8, 63
	s_ashr_i32 s9, s8, 31
	s_lshl_b64 s[8:9], s[8:9], 12
	s_add_u32 s11, s5, s8
	s_addc_u32 s10, s10, s9
	s_ashr_i32 s5, s4, 31
	s_lshl_b64 s[8:9], s[4:5], 2
	s_add_u32 s8, s11, s8
	s_addc_u32 s9, s10, s9
	v_lshl_add_u64 v[0:1], v[34:35], 2, s[8:9]
	v_lshlrev_b32_e32 v188, 2, v32
	v_lshl_add_u64 v[2:3], v[36:37], 2, s[8:9]
	v_lshl_add_u64 v[0:1], v[0:1], 0, v[188:189]
	v_lshl_add_u64 v[2:3], v[2:3], 0, v[188:189]
	global_load_dwordx4 v[4:7], v[0:1], off nt
	s_nop 0
	global_load_dwordx4 v[0:3], v[2:3], off nt
	v_readlane_b32 s41, v254, 49
	v_readlane_b32 s42, v254, 50
	v_readlane_b32 s43, v254, 51
	v_readlane_b32 s44, v254, 52
	v_readlane_b32 s45, v254, 53
	v_readlane_b32 s46, v254, 54
	v_readlane_b32 s47, v254, 55
	v_readlane_b32 s48, v254, 56
	v_readlane_b32 s49, v254, 57
	v_readlane_b32 s50, v254, 58
	v_readlane_b32 s51, v254, 59
	v_readlane_b32 s52, v254, 60
	v_readlane_b32 s53, v254, 61
.LBB0_549:
	s_or_b64 exec, exec, s[6:7]
	s_add_i32 s19, s16, 1
	s_cmpk_lt_i32 s19, 0x100
	s_cselect_b64 s[6:7], -1, 0
	s_cmpk_gt_i32 s19, 0xff
	v_mov_b32_e32 v9, 0
	v_mov_b32_e32 v10, 0
	v_mov_b32_e32 v11, 0
	v_mov_b32_e32 v12, 0
	v_mov_b32_e32 v13, 0
	v_mov_b32_e32 v14, 0
	v_mov_b32_e32 v15, 0
	s_cbranch_scc1 .LBB0_553
	s_ashr_i32 s5, s19, 31
	s_lshr_b32 s5, s5, 25
	s_add_i32 s5, s19, s5
	s_and_b32 s8, s5, 0xff80
	s_sub_i32 s8, s19, s8
	s_bfe_i32 s9, s8, 0x80000
	s_bfe_u32 s9, s9, 0x4000b
	s_add_i32 s11, s8, s9
	s_and_b32 s9, s11, 0xf0
	s_sub_i32 s8, s8, s9
	s_sext_i32_i8 s8, s8
	s_lshl_b32 s10, s8, 6
	v_or_b32_e32 v8, s10, v32
	v_cmp_gt_i32_e32 vcc, s93, v8
	v_mov_b32_e32 v15, 0
	v_mov_b32_e32 v14, 0
	v_mov_b32_e32 v13, 0
	v_mov_b32_e32 v12, 0
	v_mov_b32_e32 v11, 0
	v_mov_b32_e32 v10, 0
	v_mov_b32_e32 v9, 0
	v_mov_b32_e32 v8, 0
	s_and_saveexec_b64 s[8:9], vcc
	s_cbranch_execz .LBB0_552
	s_bfe_i32 s11, s11, 0x80000
	s_ashr_i32 s12, s5, 7
	s_sext_i32_i16 s11, s11
	s_ashr_i32 s13, s12, 31
	v_readlane_b32 s40, v254, 48
	s_lshr_b32 s11, s11, 4
	s_lshl_b64 s[12:13], s[12:13], 21
	v_readlane_b32 s54, v254, 62
	v_readlane_b32 s55, v254, 63
	s_add_u32 s5, s54, s12
	s_sext_i32_i8 s11, s11
	s_addc_u32 s14, s55, s13
	s_lshl_b32 s12, s11, 6
	s_ashr_i32 s13, s12, 31
	s_lshl_b64 s[12:13], s[12:13], 12
	s_add_u32 s5, s5, s12
	s_addc_u32 s12, s14, s13
	s_ashr_i32 s11, s10, 31
	s_lshl_b64 s[10:11], s[10:11], 2
	s_add_u32 s10, s5, s10
	s_addc_u32 s11, s12, s11
	v_lshl_add_u64 v[8:9], v[34:35], 2, s[10:11]
	v_lshlrev_b32_e32 v188, 2, v32
	v_lshl_add_u64 v[10:11], v[36:37], 2, s[10:11]
	v_lshl_add_u64 v[8:9], v[8:9], 0, v[188:189]
	v_lshl_add_u64 v[10:11], v[10:11], 0, v[188:189]
	global_load_dwordx4 v[12:15], v[8:9], off nt
	s_nop 0
	global_load_dwordx4 v[8:11], v[10:11], off nt
	v_readlane_b32 s41, v254, 49
	v_readlane_b32 s42, v254, 50
	v_readlane_b32 s43, v254, 51
	v_readlane_b32 s44, v254, 52
	v_readlane_b32 s45, v254, 53
	v_readlane_b32 s46, v254, 54
	v_readlane_b32 s47, v254, 55
	v_readlane_b32 s48, v254, 56
	v_readlane_b32 s49, v254, 57
	v_readlane_b32 s50, v254, 58
	v_readlane_b32 s51, v254, 59
	v_readlane_b32 s52, v254, 60
	v_readlane_b32 s53, v254, 61

;     ...
;         for (int q = 0; q < 4; ++q) { const int it = gi * 4 + q;
;             v[q][0] = (f32x4){0.f, 0.f, 0.f, 0.f}; v[q][1] = (f32x4){0.f, 0.f, 0.f, 0.f};
;             if (it < total) { const int b = it / per, r = it % per, k0 = (r / tn) * 64, n0 = (r % tn) * 64;
;                 const float* sp = src + (size_t)b * sbs + (size_t)k0 * N + n0; const int c4 = (tid & 15) * 4;
;                 if (n0 + c4 < N) { v[q][0] = *(const f32x4*)(sp + (size_t)(tid >> 4) * N + c4); v[q][1] = *(const f32x4*)(sp + (size_t)((tid >> 4) + 32) * N + c4); } } }
; __device__ void phase_convert(const Params& p, LAS unsigned char* lds) {
;     ...
;     cvt_job(tile, p.wba, (bf16_t*)(ws + WS_WMRG), NL, 512, 1024, 512, 0, (size_t)512 * 1024, (size_t)3 * 1024 * 512, (int)((blockIdx.x + gridDim.x - 104 % gridDim.x) % gridDim.x), (int)gridDim.x);
;     cvt_job(tile, p.wbc, (bf16_t*)(ws + WS_WMRG) + (size_t)1024 * 512, NL, 512, 1024, 512, 0, (size_t)512 * 1024, (size_t)3 * 1024 * 512, (int)((blockIdx.x + gridDim.x - 168 % gridDim.x) % gridDim.x), (int)gridDim.x);
;     cvt_job(tile, p.wbg, (bf16_t*)(ws + WS_WMRG) + (size_t)2 * 1024 * 512, NL, 512, 1024, 512, 0, (size_t)512 * 1024, (size_t)3 * 1024 * 512, (int)((blockIdx.x + gridDim.x - 232 % gridDim.x) % gridDim.x), (int)gridDim.x);
.LBB0_553:
	s_add_i32 s20, s16, 2
	s_cmpk_lt_i32 s20, 0x100
	v_mov_b32_e32 v16, 0
	s_cselect_b64 s[8:9], -1, 0
	s_cmpk_gt_i32 s20, 0xff
	v_mov_b32_e32 v20, 0
	v_mov_b32_e32 v21, 0
	v_mov_b32_e32 v22, 0
	v_mov_b32_e32 v23, 0
	v_mov_b32_e32 v24, 0
	v_mov_b32_e32 v25, 0
	v_mov_b32_e32 v26, 0
	v_mov_b32_e32 v27, 0
	s_cbranch_scc1 .LBB0_557
	s_ashr_i32 s5, s20, 31
	s_lshr_b32 s5, s5, 25
	s_add_i32 s5, s20, s5
	s_and_b32 s10, s5, 0xff80
	s_sub_i32 s10, s20, s10
	s_bfe_i32 s11, s10, 0x80000
	s_bfe_u32 s11, s11, 0x4000b
	s_add_i32 s13, s10, s11
	s_and_b32 s11, s13, 0xf0
	s_sub_i32 s10, s10, s11
	s_sext_i32_i8 s10, s10
	s_lshl_b32 s12, s10, 6
	v_or_b32_e32 v17, s12, v32
	v_cmp_gt_i32_e32 vcc, s93, v17
	v_mov_b32_e32 v27, 0
	v_mov_b32_e32 v26, 0
	v_mov_b32_e32 v25, 0
	v_mov_b32_e32 v24, 0
	v_mov_b32_e32 v23, 0
	v_mov_b32_e32 v22, 0
	v_mov_b32_e32 v21, 0
	v_mov_b32_e32 v20, 0
	s_and_saveexec_b64 s[10:11], vcc
	s_cbranch_execz .LBB0_556
	s_bfe_i32 s13, s13, 0x80000
	s_ashr_i32 s14, s5, 7
	s_sext_i32_i16 s13, s13
	s_ashr_i32 s15, s14, 31
	v_readlane_b32 s40, v254, 48
	s_lshr_b32 s13, s13, 4
	s_lshl_b64 s[14:15], s[14:15], 21
	v_readlane_b32 s54, v254, 62
	v_readlane_b32 s55, v254, 63
	s_add_u32 s5, s54, s14
	s_sext_i32_i8 s13, s13
	s_addc_u32 s21, s55, s15
	s_lshl_b32 s14, s13, 6
	s_ashr_i32 s15, s14, 31
	s_lshl_b64 s[14:15], s[14:15], 12
	s_add_u32 s5, s5, s14
	s_addc_u32 s14, s21, s15
	s_ashr_i32 s13, s12, 31
	s_lshl_b64 s[12:13], s[12:13], 2
	s_add_u32 s12, s5, s12
	s_addc_u32 s13, s14, s13
	v_lshl_add_u64 v[18:19], v[34:35], 2, s[12:13]
	v_lshlrev_b32_e32 v188, 2, v32
	v_lshl_add_u64 v[20:21], v[36:37], 2, s[12:13]
	v_lshl_add_u64 v[18:19], v[18:19], 0, v[188:189]
	v_lshl_add_u64 v[20:21], v[20:21], 0, v[188:189]
	global_load_dwordx4 v[24:27], v[18:19], off nt
	s_nop 0
	global_load_dwordx4 v[20:23], v[20:21], off nt
	v_readlane_b32 s41, v254, 49
	v_readlane_b32 s42, v254, 50
	v_readlane_b32 s43, v254, 51
	v_readlane_b32 s44, v254, 52
	v_readlane_b32 s45, v254, 53
	v_readlane_b32 s46, v254, 54
	v_readlane_b32 s47, v254, 55
	v_readlane_b32 s48, v254, 56
	v_readlane_b32 s49, v254, 57
	v_readlane_b32 s50, v254, 58
	v_readlane_b32 s51, v254, 59
	v_readlane_b32 s52, v254, 60
	v_readlane_b32 s53, v254, 61

;     ...
;         for (int q = 0; q < 4; ++q) { const int it = gi * 4 + q;
;             v[q][0] = (f32x4){0.f, 0.f, 0.f, 0.f}; v[q][1] = (f32x4){0.f, 0.f, 0.f, 0.f};
;             if (it < total) { const int b = it / per, r = it % per, k0 = (r / tn) * 64, n0 = (r % tn) * 64;
;                 const float* sp = src + (size_t)b * sbs + (size_t)k0 * N + n0; const int c4 = (tid & 15) * 4;
;                 if (n0 + c4 < N) { v[q][0] = *(const f32x4*)(sp + (size_t)(tid >> 4) * N + c4); v[q][1] = *(const f32x4*)(sp + (size_t)((tid >> 4) + 32) * N + c4); } } }
; __device__ void phase_convert(const Params& p, LAS unsigned char* lds) {
;     ...
;     cvt_job(tile, p.wba, (bf16_t*)(ws + WS_WMRG), NL, 512, 1024, 512, 0, (size_t)512 * 1024, (size_t)3 * 1024 * 512, (int)((blockIdx.x + gridDim.x - 104 % gridDim.x) % gridDim.x), (int)gridDim.x);
;     cvt_job(tile, p.wbc, (bf16_t*)(ws + WS_WMRG) + (size_t)1024 * 512, NL, 512, 1024, 512, 0, (size_t)512 * 1024, (size_t)3 * 1024 * 512, (int)((blockIdx.x + gridDim.x - 168 % gridDim.x) % gridDim.x), (int)gridDim.x);
;     cvt_job(tile, p.wbg, (bf16_t*)(ws + WS_WMRG) + (size_t)2 * 1024 * 512, NL, 512, 1024, 512, 0, (size_t)512 * 1024, (size_t)3 * 1024 * 512, (int)((blockIdx.x + gridDim.x - 232 % gridDim.x) % gridDim.x), (int)gridDim.x);
.LBB0_557:
	s_add_i32 s21, s16, 3
	s_cmpk_lt_i32 s21, 0x100
	s_cselect_b64 s[10:11], -1, 0
	s_cmpk_gt_i32 s21, 0xff
	v_mov_b32_e32 v17, 0
	v_mov_b32_e32 v18, 0
	v_mov_b32_e32 v19, 0
	v_mov_b32_e32 v28, 0
	v_mov_b32_e32 v29, 0
	v_mov_b32_e32 v30, 0
	v_mov_b32_e32 v31, 0
	s_cbranch_scc1 .LBB0_561
	s_ashr_i32 s5, s21, 31
	s_lshr_b32 s5, s5, 25
	s_add_i32 s5, s21, s5
	s_and_b32 s12, s5, 0xff80
	s_sub_i32 s12, s21, s12
	s_bfe_i32 s13, s12, 0x80000
	s_bfe_u32 s13, s13, 0x4000b
	s_add_i32 s15, s12, s13
	s_and_b32 s13, s15, 0xf0
	s_sub_i32 s12, s12, s13
	s_sext_i32_i8 s12, s12
	s_lshl_b32 s14, s12, 6
	v_or_b32_e32 v16, s14, v32
	v_cmp_gt_i32_e32 vcc, s93, v16
	v_mov_b32_e32 v31, 0
	v_mov_b32_e32 v30, 0
	v_mov_b32_e32 v29, 0
	v_mov_b32_e32 v28, 0
	v_mov_b32_e32 v19, 0
	v_mov_b32_e32 v18, 0
	v_mov_b32_e32 v17, 0
	v_mov_b32_e32 v16, 0
	s_and_saveexec_b64 s[12:13], vcc
	s_cbranch_execz .LBB0_560
	s_bfe_i32 s15, s15, 0x80000
	s_ashr_i32 s22, s5, 7
	s_sext_i32_i16 s15, s15
	s_ashr_i32 s23, s22, 31
	v_readlane_b32 s40, v254, 48
	s_lshr_b32 s15, s15, 4
	s_lshl_b64 s[22:23], s[22:23], 21
	v_readlane_b32 s54, v254, 62
	v_readlane_b32 s55, v254, 63
	s_add_u32 s5, s54, s22
	s_sext_i32_i8 s15, s15
	s_addc_u32 s24, s55, s23
	s_lshl_b32 s22, s15, 6
	s_ashr_i32 s23, s22, 31
	s_lshl_b64 s[22:23], s[22:23], 12
	s_add_u32 s5, s5, s22
	s_addc_u32 s22, s24, s23
	s_ashr_i32 s15, s14, 31
	s_lshl_b64 s[14:15], s[14:15], 2
	s_add_u32 s14, s5, s14
	s_addc_u32 s15, s22, s15
	v_lshl_add_u64 v[16:17], v[34:35], 2, s[14:15]
	v_lshlrev_b32_e32 v188, 2, v32
	v_lshl_add_u64 v[18:19], v[36:37], 2, s[14:15]
	v_lshl_add_u64 v[16:17], v[16:17], 0, v[188:189]
	v_lshl_add_u64 v[18:19], v[18:19], 0, v[188:189]
	global_load_dwordx4 v[28:31], v[16:17], off nt
	s_nop 0
	global_load_dwordx4 v[16:19], v[18:19], off nt
	v_readlane_b32 s41, v254, 49
	v_readlane_b32 s42, v254, 50
	v_readlane_b32 s43, v254, 51
	v_readlane_b32 s44, v254, 52
	v_readlane_b32 s45, v254, 53
	v_readlane_b32 s46, v254, 54
	v_readlane_b32 s47, v254, 55
	v_readlane_b32 s48, v254, 56
	v_readlane_b32 s49, v254, 57
	v_readlane_b32 s50, v254, 58
	v_readlane_b32 s51, v254, 59
	v_readlane_b32 s52, v254, 60
	v_readlane_b32 s53, v254, 61

;     ...
;     for (int gi = bid; gi * 4 < total; gi += nb) {
;         f32x4 v[4][2];
; #pragma unroll
;         for (int q = 0; q < 4; ++q) { const int it = gi * 4 + q;
;             v[q][0] = (f32x4){0.f, 0.f, 0.f, 0.f}; v[q][1] = (f32x4){0.f, 0.f, 0.f, 0.f};
;             if (it < total) { const int b = it / per, r = it % per, k0 = (r / tn) * 64, n0 = (r % tn) * 64;
;                 const float* sp = src + (size_t)b * sbs + (size_t)k0 * N + n0; const int c4 = (tid & 15) * 4;
;                 if (n0 + c4 < N) { v[q][0] = *(const f32x4*)(sp + (size_t)(tid >> 4) * N + c4); v[q][1] = *(const f32x4*)(sp + (size_t)((tid >> 4) + 32) * N + c4); } } }
.LBB0_578:
	s_ashr_i32 s4, s16, 31
	s_lshr_b32 s4, s4, 25
	s_add_i32 s4, s16, s4
	s_and_b32 s4, s4, 0xff80
	s_sub_i32 s4, s16, s4
	s_bfe_i32 s5, s4, 0x80000
	s_bfe_u32 s5, s5, 0x4000b
	s_add_i32 s18, s4, s5
	s_and_b32 s5, s18, 0xf0
	s_sub_i32 s4, s4, s5
	s_sext_i32_i8 s4, s4
	s_lshl_b32 s4, s4, 6
	v_or_b32_e32 v0, s4, v32
	v_cmp_gt_i32_e32 vcc, s93, v0
	v_mov_b32_e32 v8, 0
	v_mov_b32_e32 v0, 0
	v_mov_b32_e32 v1, 0
	v_mov_b32_e32 v2, 0
	v_mov_b32_e32 v3, 0
	v_mov_b32_e32 v4, 0
	v_mov_b32_e32 v5, 0
	v_mov_b32_e32 v6, 0
	v_mov_b32_e32 v7, 0
	s_and_saveexec_b64 s[6:7], vcc
	s_cbranch_execz .LBB0_580
	s_ashr_i32 s5, s17, 31
	s_lshr_b32 s5, s5, 27
	s_add_i32 s5, s17, s5
	s_ashr_i32 s8, s5, 5
	s_ashr_i32 s9, s8, 31
	s_lshl_b64 s[8:9], s[8:9], 21
	v_readlane_b32 s40, v252, 40
	v_readlane_b32 s41, v252, 41
	s_add_u32 s5, s40, s8
	s_addc_u32 s10, s41, s9
	s_bfe_i32 s8, s18, 0x80000
	s_sext_i32_i16 s8, s8
	s_lshl_b32 s8, s8, 2
	s_andn2_b32 s8, s8, 63
	s_ashr_i32 s9, s8, 31
	s_lshl_b64 s[8:9], s[8:9], 12
	s_add_u32 s11, s5, s8
	s_addc_u32 s10, s10, s9
	s_ashr_i32 s5, s4, 31
	s_lshl_b64 s[8:9], s[4:5], 2
	s_add_u32 s8, s11, s8
	s_addc_u32 s9, s10, s9
	v_lshl_add_u64 v[0:1], v[34:35], 2, s[8:9]
	v_lshlrev_b32_e32 v188, 2, v32
	v_lshl_add_u64 v[2:3], v[36:37], 2, s[8:9]
	v_lshl_add_u64 v[0:1], v[0:1], 0, v[188:189]
	v_lshl_add_u64 v[2:3], v[2:3], 0, v[188:189]
	global_load_dwordx4 v[4:7], v[0:1], off nt
	s_nop 0
	global_load_dwordx4 v[0:3], v[2:3], off nt
	v_readlane_b32 s42, v252, 42
	v_readlane_b32 s43, v252, 43
	v_readlane_b32 s44, v252, 44
	v_readlane_b32 s45, v252, 45
	v_readlane_b32 s46, v252, 46
	v_readlane_b32 s47, v252, 47
	v_readlane_b32 s48, v252, 48
	v_readlane_b32 s49, v252, 49
	v_readlane_b32 s50, v252, 50
	v_readlane_b32 s51, v252, 51
	v_readlane_b32 s52, v252, 52
	v_readlane_b32 s53, v252, 53
	v_readlane_b32 s54, v252, 54
	v_readlane_b32 s55, v252, 55
.LBB0_580:
	s_or_b64 exec, exec, s[6:7]
	s_add_i32 s19, s16, 1
	s_cmpk_lt_i32 s19, 0x100
	s_cselect_b64 s[6:7], -1, 0
	s_cmpk_gt_i32 s19, 0xff
	v_mov_b32_e32 v9, 0
	v_mov_b32_e32 v10, 0
	v_mov_b32_e32 v11, 0
	v_mov_b32_e32 v12, 0
	v_mov_b32_e32 v13, 0
	v_mov_b32_e32 v14, 0
	v_mov_b32_e32 v15, 0
	s_cbranch_scc1 .LBB0_584
	s_ashr_i32 s5, s19, 31
	s_lshr_b32 s5, s5, 25
	s_add_i32 s5, s19, s5
	s_and_b32 s8, s5, 0xff80
	s_sub_i32 s8, s19, s8
	s_bfe_i32 s9, s8, 0x80000
	s_bfe_u32 s9, s9, 0x4000b
	s_add_i32 s11, s8, s9
	s_and_b32 s9, s11, 0xf0
	s_sub_i32 s8, s8, s9
	s_sext_i32_i8 s8, s8
	s_lshl_b32 s10, s8, 6
	v_or_b32_e32 v8, s10, v32
	v_cmp_gt_i32_e32 vcc, s93, v8
	v_mov_b32_e32 v15, 0
	v_mov_b32_e32 v14, 0
	v_mov_b32_e32 v13, 0
	v_mov_b32_e32 v12, 0
	v_mov_b32_e32 v11, 0
	v_mov_b32_e32 v10, 0
	v_mov_b32_e32 v9, 0
	v_mov_b32_e32 v8, 0
	s_and_saveexec_b64 s[8:9], vcc
	s_cbranch_execz .LBB0_583
	s_bfe_i32 s11, s11, 0x80000
	s_ashr_i32 s12, s5, 7
	s_sext_i32_i16 s11, s11
	s_ashr_i32 s13, s12, 31
	s_lshr_b32 s11, s11, 4
	s_lshl_b64 s[12:13], s[12:13], 21
	v_readlane_b32 s40, v252, 40
	v_readlane_b32 s41, v252, 41
	s_add_u32 s5, s40, s12
	s_sext_i32_i8 s11, s11
	s_addc_u32 s14, s41, s13
	s_lshl_b32 s12, s11, 6
	s_ashr_i32 s13, s12, 31
	s_lshl_b64 s[12:13], s[12:13], 12
	s_add_u32 s5, s5, s12
	s_addc_u32 s12, s14, s13
	s_ashr_i32 s11, s10, 31
	s_lshl_b64 s[10:11], s[10:11], 2
	s_add_u32 s10, s5, s10
	s_addc_u32 s11, s12, s11
	v_lshl_add_u64 v[8:9], v[34:35], 2, s[10:11]
	v_lshlrev_b32_e32 v188, 2, v32
	v_lshl_add_u64 v[10:11], v[36:37], 2, s[10:11]
	v_lshl_add_u64 v[8:9], v[8:9], 0, v[188:189]
	v_lshl_add_u64 v[10:11], v[10:11], 0, v[188:189]
	global_load_dwordx4 v[12:15], v[8:9], off nt
	s_nop 0
	global_load_dwordx4 v[8:11], v[10:11], off nt
	v_readlane_b32 s42, v252, 42
	v_readlane_b32 s43, v252, 43
	v_readlane_b32 s44, v252, 44
	v_readlane_b32 s45, v252, 45
	v_readlane_b32 s46, v252, 46
	v_readlane_b32 s47, v252, 47
	v_readlane_b32 s48, v252, 48
	v_readlane_b32 s49, v252, 49
	v_readlane_b32 s50, v252, 50
	v_readlane_b32 s51, v252, 51
	v_readlane_b32 s52, v252, 52
	v_readlane_b32 s53, v252, 53
	v_readlane_b32 s54, v252, 54
	v_readlane_b32 s55, v252, 55

;     ...
;         for (int q = 0; q < 4; ++q) { const int it = gi * 4 + q;
;             v[q][0] = (f32x4){0.f, 0.f, 0.f, 0.f}; v[q][1] = (f32x4){0.f, 0.f, 0.f, 0.f};
;             if (it < total) { const int b = it / per, r = it % per, k0 = (r / tn) * 64, n0 = (r % tn) * 64;
;                 const float* sp = src + (size_t)b * sbs + (size_t)k0 * N + n0; const int c4 = (tid & 15) * 4;
;                 if (n0 + c4 < N) { v[q][0] = *(const f32x4*)(sp + (size_t)(tid >> 4) * N + c4); v[q][1] = *(const f32x4*)(sp + (size_t)((tid >> 4) + 32) * N + c4); } } }
.LBB0_584:
	s_add_i32 s20, s16, 2
	s_cmpk_lt_i32 s20, 0x100
	v_mov_b32_e32 v16, 0
	s_cselect_b64 s[8:9], -1, 0
	s_cmpk_gt_i32 s20, 0xff
	v_mov_b32_e32 v20, 0
	v_mov_b32_e32 v21, 0
	v_mov_b32_e32 v22, 0
	v_mov_b32_e32 v23, 0
	v_mov_b32_e32 v24, 0
	v_mov_b32_e32 v25, 0
	v_mov_b32_e32 v26, 0
	v_mov_b32_e32 v27, 0
	s_cbranch_scc1 .LBB0_588
	s_ashr_i32 s5, s20, 31
	s_lshr_b32 s5, s5, 25
	s_add_i32 s5, s20, s5
	s_and_b32 s10, s5, 0xff80
	s_sub_i32 s10, s20, s10
	s_bfe_i32 s11, s10, 0x80000
	s_bfe_u32 s11, s11, 0x4000b
	s_add_i32 s13, s10, s11
	s_and_b32 s11, s13, 0xf0
	s_sub_i32 s10, s10, s11
	s_sext_i32_i8 s10, s10
	s_lshl_b32 s12, s10, 6
	v_or_b32_e32 v17, s12, v32
	v_cmp_gt_i32_e32 vcc, s93, v17
	v_mov_b32_e32 v27, 0
	v_mov_b32_e32 v26, 0
	v_mov_b32_e32 v25, 0
	v_mov_b32_e32 v24, 0
	v_mov_b32_e32 v23, 0
	v_mov_b32_e32 v22, 0
	v_mov_b32_e32 v21, 0
	v_mov_b32_e32 v20, 0
	s_and_saveexec_b64 s[10:11], vcc
	s_cbranch_execz .LBB0_587
	s_bfe_i32 s13, s13, 0x80000
	s_ashr_i32 s14, s5, 7
	s_sext_i32_i16 s13, s13
	s_ashr_i32 s15, s14, 31
	s_lshr_b32 s13, s13, 4
	s_lshl_b64 s[14:15], s[14:15], 21
	v_readlane_b32 s40, v252, 40
	v_readlane_b32 s41, v252, 41
	s_add_u32 s5, s40, s14
	s_sext_i32_i8 s13, s13
	s_addc_u32 s21, s41, s15
	s_lshl_b32 s14, s13, 6
	s_ashr_i32 s15, s14, 31
	s_lshl_b64 s[14:15], s[14:15], 12
	s_add_u32 s5, s5, s14
	s_addc_u32 s14, s21, s15
	s_ashr_i32 s13, s12, 31
	s_lshl_b64 s[12:13], s[12:13], 2
	s_add_u32 s12, s5, s12
	s_addc_u32 s13, s14, s13
	v_lshl_add_u64 v[18:19], v[34:35], 2, s[12:13]
	v_lshlrev_b32_e32 v188, 2, v32
	v_lshl_add_u64 v[20:21], v[36:37], 2, s[12:13]
	v_lshl_add_u64 v[18:19], v[18:19], 0, v[188:189]
	v_lshl_add_u64 v[20:21], v[20:21], 0, v[188:189]
	global_load_dwordx4 v[24:27], v[18:19], off nt
	s_nop 0
	global_load_dwordx4 v[20:23], v[20:21], off nt
	v_readlane_b32 s42, v252, 42
	v_readlane_b32 s43, v252, 43
	v_readlane_b32 s44, v252, 44
	v_readlane_b32 s45, v252, 45
	v_readlane_b32 s46, v252, 46
	v_readlane_b32 s47, v252, 47
	v_readlane_b32 s48, v252, 48
	v_readlane_b32 s49, v252, 49
	v_readlane_b32 s50, v252, 50
	v_readlane_b32 s51, v252, 51
	v_readlane_b32 s52, v252, 52
	v_readlane_b32 s53, v252, 53
	v_readlane_b32 s54, v252, 54
	v_readlane_b32 s55, v252, 55

;     ...
;         for (int q = 0; q < 4; ++q) { const int it = gi * 4 + q;
;             v[q][0] = (f32x4){0.f, 0.f, 0.f, 0.f}; v[q][1] = (f32x4){0.f, 0.f, 0.f, 0.f};
;             if (it < total) { const int b = it / per, r = it % per, k0 = (r / tn) * 64, n0 = (r % tn) * 64;
;                 const float* sp = src + (size_t)b * sbs + (size_t)k0 * N + n0; const int c4 = (tid & 15) * 4;
;                 if (n0 + c4 < N) { v[q][0] = *(const f32x4*)(sp + (size_t)(tid >> 4) * N + c4); v[q][1] = *(const f32x4*)(sp + (size_t)((tid >> 4) + 32) * N + c4); } } }
.LBB0_588:
	s_add_i32 s21, s16, 3
	s_cmpk_lt_i32 s21, 0x100
	s_cselect_b64 s[10:11], -1, 0
	s_cmpk_gt_i32 s21, 0xff
	v_mov_b32_e32 v17, 0
	v_mov_b32_e32 v18, 0
	v_mov_b32_e32 v19, 0
	v_mov_b32_e32 v28, 0
	v_mov_b32_e32 v29, 0
	v_mov_b32_e32 v30, 0
	v_mov_b32_e32 v31, 0
	s_cbranch_scc1 .LBB0_592
	s_ashr_i32 s5, s21, 31
	s_lshr_b32 s5, s5, 25
	s_add_i32 s5, s21, s5
	s_and_b32 s12, s5, 0xff80
	s_sub_i32 s12, s21, s12
	s_bfe_i32 s13, s12, 0x80000
	s_bfe_u32 s13, s13, 0x4000b
	s_add_i32 s15, s12, s13
	s_and_b32 s13, s15, 0xf0
	s_sub_i32 s12, s12, s13
	s_sext_i32_i8 s12, s12
	s_lshl_b32 s14, s12, 6
	v_or_b32_e32 v16, s14, v32
	v_cmp_gt_i32_e32 vcc, s93, v16
	v_mov_b32_e32 v31, 0
	v_mov_b32_e32 v30, 0
	v_mov_b32_e32 v29, 0
	v_mov_b32_e32 v28, 0
	v_mov_b32_e32 v19, 0
	v_mov_b32_e32 v18, 0
	v_mov_b32_e32 v17, 0
	v_mov_b32_e32 v16, 0
	s_and_saveexec_b64 s[12:13], vcc
	s_cbranch_execz .LBB0_591
	s_bfe_i32 s15, s15, 0x80000
	s_ashr_i32 s22, s5, 7
	s_sext_i32_i16 s15, s15
	s_ashr_i32 s23, s22, 31
	s_lshr_b32 s15, s15, 4
	s_lshl_b64 s[22:23], s[22:23], 21
	v_readlane_b32 s40, v252, 40
	v_readlane_b32 s41, v252, 41
	s_add_u32 s5, s40, s22
	s_sext_i32_i8 s15, s15
	s_addc_u32 s24, s41, s23
	s_lshl_b32 s22, s15, 6
	s_ashr_i32 s23, s22, 31
	s_lshl_b64 s[22:23], s[22:23], 12
	s_add_u32 s5, s5, s22
	s_addc_u32 s22, s24, s23
	s_ashr_i32 s15, s14, 31
	s_lshl_b64 s[14:15], s[14:15], 2
	s_add_u32 s14, s5, s14
	s_addc_u32 s15, s22, s15
	v_lshl_add_u64 v[16:17], v[34:35], 2, s[14:15]
	v_lshlrev_b32_e32 v188, 2, v32
	v_lshl_add_u64 v[18:19], v[36:37], 2, s[14:15]
	v_lshl_add_u64 v[16:17], v[16:17], 0, v[188:189]
	v_lshl_add_u64 v[18:19], v[18:19], 0, v[188:189]
	global_load_dwordx4 v[28:31], v[16:17], off nt
	s_nop 0
	global_load_dwordx4 v[16:19], v[18:19], off nt
	v_readlane_b32 s42, v252, 42
	v_readlane_b32 s43, v252, 43
	v_readlane_b32 s44, v252, 44
	v_readlane_b32 s45, v252, 45
	v_readlane_b32 s46, v252, 46
	v_readlane_b32 s47, v252, 47
	v_readlane_b32 s48, v252, 48
	v_readlane_b32 s49, v252, 49
	v_readlane_b32 s50, v252, 50
	v_readlane_b32 s51, v252, 51
	v_readlane_b32 s52, v252, 52
	v_readlane_b32 s53, v252, 53
	v_readlane_b32 s54, v252, 54
	v_readlane_b32 s55, v252, 55

;     ...
;     for (int gi = bid; gi * 4 < total; gi += nb) {
;         f32x4 v[4][2];
; #pragma unroll
;         for (int q = 0; q < 4; ++q) { const int it = gi * 4 + q;
;             v[q][0] = (f32x4){0.f, 0.f, 0.f, 0.f}; v[q][1] = (f32x4){0.f, 0.f, 0.f, 0.f};
;             if (it < total) { const int b = it / per, r = it % per, k0 = (r / tn) * 64, n0 = (r % tn) * 64;
;                 const float* sp = src + (size_t)b * sbs + (size_t)k0 * N + n0; const int c4 = (tid & 15) * 4;
;                 if (n0 + c4 < N) { v[q][0] = *(const f32x4*)(sp + (size_t)(tid >> 4) * N + c4); v[q][1] = *(const f32x4*)(sp + (size_t)((tid >> 4) + 32) * N + c4); } } }
.LBB0_609:
	s_ashr_i32 s4, s16, 31
	s_lshr_b32 s4, s4, 25
	s_add_i32 s4, s16, s4
	s_and_b32 s4, s4, 0xff80
	s_sub_i32 s4, s16, s4
	s_bfe_i32 s5, s4, 0x80000
	s_bfe_u32 s5, s5, 0x4000b
	s_add_i32 s18, s4, s5
	s_and_b32 s5, s18, 0xf0
	s_sub_i32 s4, s4, s5
	s_sext_i32_i8 s4, s4
	s_lshl_b32 s4, s4, 6
	v_or_b32_e32 v0, s4, v32
	v_cmp_gt_i32_e32 vcc, s93, v0
	v_mov_b32_e32 v8, 0
	v_mov_b32_e32 v0, 0
	v_mov_b32_e32 v1, 0
	v_mov_b32_e32 v2, 0
	v_mov_b32_e32 v3, 0
	v_mov_b32_e32 v4, 0
	v_mov_b32_e32 v5, 0
	v_mov_b32_e32 v6, 0
	v_mov_b32_e32 v7, 0
	s_and_saveexec_b64 s[6:7], vcc
	s_cbranch_execz .LBB0_611
	s_ashr_i32 s5, s17, 31
	s_lshr_b32 s5, s5, 27
	s_add_i32 s5, s17, s5
	s_ashr_i32 s8, s5, 5
	s_ashr_i32 s9, s8, 31
	v_readlane_b32 s40, v252, 40
	s_lshl_b64 s[8:9], s[8:9], 21
	v_readlane_b32 s42, v252, 42
	v_readlane_b32 s43, v252, 43
	s_add_u32 s5, s42, s8
	s_addc_u32 s10, s43, s9
	s_bfe_i32 s8, s18, 0x80000
	s_sext_i32_i16 s8, s8
	s_lshl_b32 s8, s8, 2
	s_andn2_b32 s8, s8, 63
	s_ashr_i32 s9, s8, 31
	s_lshl_b64 s[8:9], s[8:9], 12
	s_add_u32 s11, s5, s8
	s_addc_u32 s10, s10, s9
	s_ashr_i32 s5, s4, 31
	s_lshl_b64 s[8:9], s[4:5], 2
	s_add_u32 s8, s11, s8
	s_addc_u32 s9, s10, s9
	v_lshl_add_u64 v[0:1], v[34:35], 2, s[8:9]
	v_lshlrev_b32_e32 v188, 2, v32
	v_lshl_add_u64 v[2:3], v[36:37], 2, s[8:9]
	v_lshl_add_u64 v[0:1], v[0:1], 0, v[188:189]
	v_lshl_add_u64 v[2:3], v[2:3], 0, v[188:189]
	global_load_dwordx4 v[4:7], v[0:1], off nt
	s_nop 0
	global_load_dwordx4 v[0:3], v[2:3], off nt
	v_readlane_b32 s41, v252, 41
	v_readlane_b32 s44, v252, 44
	v_readlane_b32 s45, v252, 45
	v_readlane_b32 s46, v252, 46
	v_readlane_b32 s47, v252, 47
	v_readlane_b32 s48, v252, 48
	v_readlane_b32 s49, v252, 49
	v_readlane_b32 s50, v252, 50
	v_readlane_b32 s51, v252, 51
	v_readlane_b32 s52, v252, 52
	v_readlane_b32 s53, v252, 53
	v_readlane_b32 s54, v252, 54
	v_readlane_b32 s55, v252, 55
.LBB0_611:
	s_or_b64 exec, exec, s[6:7]
	s_add_i32 s19, s16, 1
	s_cmpk_lt_i32 s19, 0x100
	s_cselect_b64 s[6:7], -1, 0
	s_cmpk_gt_i32 s19, 0xff
	v_mov_b32_e32 v9, 0
	v_mov_b32_e32 v10, 0
	v_mov_b32_e32 v11, 0
	v_mov_b32_e32 v12, 0
	v_mov_b32_e32 v13, 0
	v_mov_b32_e32 v14, 0
	v_mov_b32_e32 v15, 0
	s_cbranch_scc1 .LBB0_615
	s_ashr_i32 s5, s19, 31
	s_lshr_b32 s5, s5, 25
	s_add_i32 s5, s19, s5
	s_and_b32 s8, s5, 0xff80
	s_sub_i32 s8, s19, s8
	s_bfe_i32 s9, s8, 0x80000
	s_bfe_u32 s9, s9, 0x4000b
	s_add_i32 s11, s8, s9
	s_and_b32 s9, s11, 0xf0
	s_sub_i32 s8, s8, s9
	s_sext_i32_i8 s8, s8
	s_lshl_b32 s10, s8, 6
	v_or_b32_e32 v8, s10, v32
	v_cmp_gt_i32_e32 vcc, s93, v8
	v_mov_b32_e32 v15, 0
	v_mov_b32_e32 v14, 0
	v_mov_b32_e32 v13, 0
	v_mov_b32_e32 v12, 0
	v_mov_b32_e32 v11, 0
	v_mov_b32_e32 v10, 0
	v_mov_b32_e32 v9, 0
	v_mov_b32_e32 v8, 0
	s_and_saveexec_b64 s[8:9], vcc
	s_cbranch_execz .LBB0_614
	s_bfe_i32 s11, s11, 0x80000
	s_ashr_i32 s12, s5, 7
	s_sext_i32_i16 s11, s11
	s_ashr_i32 s13, s12, 31
	v_readlane_b32 s40, v252, 40
	s_lshr_b32 s11, s11, 4
	s_lshl_b64 s[12:13], s[12:13], 21
	v_readlane_b32 s42, v252, 42
	v_readlane_b32 s43, v252, 43
	s_add_u32 s5, s42, s12
	s_sext_i32_i8 s11, s11
	s_addc_u32 s14, s43, s13
	s_lshl_b32 s12, s11, 6
	s_ashr_i32 s13, s12, 31
	s_lshl_b64 s[12:13], s[12:13], 12
	s_add_u32 s5, s5, s12
	s_addc_u32 s12, s14, s13
	s_ashr_i32 s11, s10, 31
	s_lshl_b64 s[10:11], s[10:11], 2
	s_add_u32 s10, s5, s10
	s_addc_u32 s11, s12, s11
	v_lshl_add_u64 v[8:9], v[34:35], 2, s[10:11]
	v_lshlrev_b32_e32 v188, 2, v32
	v_lshl_add_u64 v[10:11], v[36:37], 2, s[10:11]
	v_lshl_add_u64 v[8:9], v[8:9], 0, v[188:189]
	v_lshl_add_u64 v[10:11], v[10:11], 0, v[188:189]
	global_load_dwordx4 v[12:15], v[8:9], off nt
	s_nop 0
	global_load_dwordx4 v[8:11], v[10:11], off nt
	v_readlane_b32 s41, v252, 41
	v_readlane_b32 s44, v252, 44
	v_readlane_b32 s45, v252, 45
	v_readlane_b32 s46, v252, 46
	v_readlane_b32 s47, v252, 47
	v_readlane_b32 s48, v252, 48
	v_readlane_b32 s49, v252, 49
	v_readlane_b32 s50, v252, 50
	v_readlane_b32 s51, v252, 51
	v_readlane_b32 s52, v252, 52
	v_readlane_b32 s53, v252, 53
	v_readlane_b32 s54, v252, 54
	v_readlane_b32 s55, v252, 55

;     ...
;         for (int q = 0; q < 4; ++q) { const int it = gi * 4 + q;
;             v[q][0] = (f32x4){0.f, 0.f, 0.f, 0.f}; v[q][1] = (f32x4){0.f, 0.f, 0.f, 0.f};
;             if (it < total) { const int b = it / per, r = it % per, k0 = (r / tn) * 64, n0 = (r % tn) * 64;
;                 const float* sp = src + (size_t)b * sbs + (size_t)k0 * N + n0; const int c4 = (tid & 15) * 4;
;                 if (n0 + c4 < N) { v[q][0] = *(const f32x4*)(sp + (size_t)(tid >> 4) * N + c4); v[q][1] = *(const f32x4*)(sp + (size_t)((tid >> 4) + 32) * N + c4); } } }
.LBB0_615:
	s_add_i32 s20, s16, 2
	s_cmpk_lt_i32 s20, 0x100
	v_mov_b32_e32 v16, 0
	s_cselect_b64 s[8:9], -1, 0
	s_cmpk_gt_i32 s20, 0xff
	v_mov_b32_e32 v20, 0
	v_mov_b32_e32 v21, 0
	v_mov_b32_e32 v22, 0
	v_mov_b32_e32 v23, 0
	v_mov_b32_e32 v24, 0
	v_mov_b32_e32 v25, 0
	v_mov_b32_e32 v26, 0
	v_mov_b32_e32 v27, 0
	s_cbranch_scc1 .LBB0_619
	s_ashr_i32 s5, s20, 31
	s_lshr_b32 s5, s5, 25
	s_add_i32 s5, s20, s5
	s_and_b32 s10, s5, 0xff80
	s_sub_i32 s10, s20, s10
	s_bfe_i32 s11, s10, 0x80000
	s_bfe_u32 s11, s11, 0x4000b
	s_add_i32 s13, s10, s11
	s_and_b32 s11, s13, 0xf0
	s_sub_i32 s10, s10, s11
	s_sext_i32_i8 s10, s10
	s_lshl_b32 s12, s10, 6
	v_or_b32_e32 v17, s12, v32
	v_cmp_gt_i32_e32 vcc, s93, v17
	v_mov_b32_e32 v27, 0
	v_mov_b32_e32 v26, 0
	v_mov_b32_e32 v25, 0
	v_mov_b32_e32 v24, 0
	v_mov_b32_e32 v23, 0
	v_mov_b32_e32 v22, 0
	v_mov_b32_e32 v21, 0
	v_mov_b32_e32 v20, 0
	s_and_saveexec_b64 s[10:11], vcc
	s_cbranch_execz .LBB0_618
	s_bfe_i32 s13, s13, 0x80000
	s_ashr_i32 s14, s5, 7
	s_sext_i32_i16 s13, s13
	s_ashr_i32 s15, s14, 31
	v_readlane_b32 s40, v252, 40
	s_lshr_b32 s13, s13, 4
	s_lshl_b64 s[14:15], s[14:15], 21
	v_readlane_b32 s42, v252, 42
	v_readlane_b32 s43, v252, 43
	s_add_u32 s5, s42, s14
	s_sext_i32_i8 s13, s13
	s_addc_u32 s21, s43, s15
	s_lshl_b32 s14, s13, 6
	s_ashr_i32 s15, s14, 31
	s_lshl_b64 s[14:15], s[14:15], 12
	s_add_u32 s5, s5, s14
	s_addc_u32 s14, s21, s15
	s_ashr_i32 s13, s12, 31
	s_lshl_b64 s[12:13], s[12:13], 2
	s_add_u32 s12, s5, s12
	s_addc_u32 s13, s14, s13
	v_lshl_add_u64 v[18:19], v[34:35], 2, s[12:13]
	v_lshlrev_b32_e32 v188, 2, v32
	v_lshl_add_u64 v[20:21], v[36:37], 2, s[12:13]
	v_lshl_add_u64 v[18:19], v[18:19], 0, v[188:189]
	v_lshl_add_u64 v[20:21], v[20:21], 0, v[188:189]
	global_load_dwordx4 v[24:27], v[18:19], off nt
	s_nop 0
	global_load_dwordx4 v[20:23], v[20:21], off nt
	v_readlane_b32 s41, v252, 41
	v_readlane_b32 s44, v252, 44
	v_readlane_b32 s45, v252, 45
	v_readlane_b32 s46, v252, 46
	v_readlane_b32 s47, v252, 47
	v_readlane_b32 s48, v252, 48
	v_readlane_b32 s49, v252, 49
	v_readlane_b32 s50, v252, 50
	v_readlane_b32 s51, v252, 51
	v_readlane_b32 s52, v252, 52
	v_readlane_b32 s53, v252, 53
	v_readlane_b32 s54, v252, 54
	v_readlane_b32 s55, v252, 55

;     ...
;         for (int q = 0; q < 4; ++q) { const int it = gi * 4 + q;
;             v[q][0] = (f32x4){0.f, 0.f, 0.f, 0.f}; v[q][1] = (f32x4){0.f, 0.f, 0.f, 0.f};
;             if (it < total) { const int b = it / per, r = it % per, k0 = (r / tn) * 64, n0 = (r % tn) * 64;
;                 const float* sp = src + (size_t)b * sbs + (size_t)k0 * N + n0; const int c4 = (tid & 15) * 4;
;                 if (n0 + c4 < N) { v[q][0] = *(const f32x4*)(sp + (size_t)(tid >> 4) * N + c4); v[q][1] = *(const f32x4*)(sp + (size_t)((tid >> 4) + 32) * N + c4); } } }
.LBB0_619:
	s_add_i32 s21, s16, 3
	s_cmpk_lt_i32 s21, 0x100
	s_cselect_b64 s[10:11], -1, 0
	s_cmpk_gt_i32 s21, 0xff
	v_mov_b32_e32 v17, 0
	v_mov_b32_e32 v18, 0
	v_mov_b32_e32 v19, 0
	v_mov_b32_e32 v28, 0
	v_mov_b32_e32 v29, 0
	v_mov_b32_e32 v30, 0
	v_mov_b32_e32 v31, 0
	s_cbranch_scc1 .LBB0_623
	s_ashr_i32 s5, s21, 31
	s_lshr_b32 s5, s5, 25
	s_add_i32 s5, s21, s5
	s_and_b32 s12, s5, 0xff80
	s_sub_i32 s12, s21, s12
	s_bfe_i32 s13, s12, 0x80000
	s_bfe_u32 s13, s13, 0x4000b
	s_add_i32 s15, s12, s13
	s_and_b32 s13, s15, 0xf0
	s_sub_i32 s12, s12, s13
	s_sext_i32_i8 s12, s12
	s_lshl_b32 s14, s12, 6
	v_or_b32_e32 v16, s14, v32
	v_cmp_gt_i32_e32 vcc, s93, v16
	v_mov_b32_e32 v31, 0
	v_mov_b32_e32 v30, 0
	v_mov_b32_e32 v29, 0
	v_mov_b32_e32 v28, 0
	v_mov_b32_e32 v19, 0
	v_mov_b32_e32 v18, 0
	v_mov_b32_e32 v17, 0
	v_mov_b32_e32 v16, 0
	s_and_saveexec_b64 s[12:13], vcc
	s_cbranch_execz .LBB0_622
	s_bfe_i32 s15, s15, 0x80000
	s_ashr_i32 s22, s5, 7
	s_sext_i32_i16 s15, s15
	s_ashr_i32 s23, s22, 31
	v_readlane_b32 s40, v252, 40
	s_lshr_b32 s15, s15, 4
	s_lshl_b64 s[22:23], s[22:23], 21
	v_readlane_b32 s42, v252, 42
	v_readlane_b32 s43, v252, 43
	s_add_u32 s5, s42, s22
	s_sext_i32_i8 s15, s15
	s_addc_u32 s24, s43, s23
	s_lshl_b32 s22, s15, 6
	s_ashr_i32 s23, s22, 31
	s_lshl_b64 s[22:23], s[22:23], 12
	s_add_u32 s5, s5, s22
	s_addc_u32 s22, s24, s23
	s_ashr_i32 s15, s14, 31
	s_lshl_b64 s[14:15], s[14:15], 2
	s_add_u32 s14, s5, s14
	s_addc_u32 s15, s22, s15
	v_lshl_add_u64 v[16:17], v[34:35], 2, s[14:15]
	v_lshlrev_b32_e32 v188, 2, v32
	v_lshl_add_u64 v[18:19], v[36:37], 2, s[14:15]
	v_lshl_add_u64 v[16:17], v[16:17], 0, v[188:189]
	v_lshl_add_u64 v[18:19], v[18:19], 0, v[188:189]
	global_load_dwordx4 v[28:31], v[16:17], off nt
	s_nop 0
	global_load_dwordx4 v[16:19], v[18:19], off nt
	v_readlane_b32 s41, v252, 41
	v_readlane_b32 s44, v252, 44
	v_readlane_b32 s45, v252, 45
	v_readlane_b32 s46, v252, 46
	v_readlane_b32 s47, v252, 47
	v_readlane_b32 s48, v252, 48
	v_readlane_b32 s49, v252, 49
	v_readlane_b32 s50, v252, 50
	v_readlane_b32 s51, v252, 51
	v_readlane_b32 s52, v252, 52
	v_readlane_b32 s53, v252, 53
	v_readlane_b32 s54, v252, 54
	v_readlane_b32 s55, v252, 55

;     ...
;     for (int gi = bid; gi * 4 < total; gi += nb) {
;         f32x4 v[4][2];
; #pragma unroll
;         for (int q = 0; q < 4; ++q) { const int it = gi * 4 + q;
;             v[q][0] = (f32x4){0.f, 0.f, 0.f, 0.f}; v[q][1] = (f32x4){0.f, 0.f, 0.f, 0.f};
;             if (it < total) { const int b = it / per, r = it % per, k0 = (r / tn) * 64, n0 = (r % tn) * 64;
;                 const float* sp = src + (size_t)b * sbs + (size_t)k0 * N + n0; const int c4 = (tid & 15) * 4;
;                 if (n0 + c4 < N) { v[q][0] = *(const f32x4*)(sp + (size_t)(tid >> 4) * N + c4); v[q][1] = *(const f32x4*)(sp + (size_t)((tid >> 4) + 32) * N + c4); } } }
.LBB0_640:
	s_ashr_i32 s4, s16, 31
	s_lshr_b32 s4, s4, 24
	s_add_i32 s4, s16, s4
	s_and_b32 s4, s4, 0xffffff00
	s_sub_i32 s4, s16, s4
	s_sext_i32_i16 s5, s4
	s_bfe_u32 s5, s5, 0x4001b
	s_add_i32 s18, s4, s5
	s_and_b32 s5, s18, 0xfff0
	s_sub_i32 s4, s4, s5
	s_sext_i32_i16 s4, s4
	s_lshl_b32 s4, s4, 6
	v_or_b32_e32 v0, s4, v32
	v_cmp_gt_i32_e32 vcc, s93, v0
	v_mov_b32_e32 v8, 0
	v_mov_b32_e32 v0, 0
	v_mov_b32_e32 v1, 0
	v_mov_b32_e32 v2, 0
	v_mov_b32_e32 v3, 0
	v_mov_b32_e32 v4, 0
	v_mov_b32_e32 v5, 0
	v_mov_b32_e32 v6, 0
	v_mov_b32_e32 v7, 0
	s_and_saveexec_b64 s[6:7], vcc
	s_cbranch_execz .LBB0_642
	s_ashr_i32 s5, s17, 31
	s_lshr_b32 s5, s5, 26
	s_add_i32 s5, s17, s5
	s_ashr_i32 s8, s5, 6
	s_ashr_i32 s9, s8, 31
	v_readlane_b32 s40, v252, 40
	s_lshl_b64 s[8:9], s[8:9], 22
	v_readlane_b32 s44, v252, 44
	v_readlane_b32 s45, v252, 45
	s_add_u32 s5, s44, s8
	s_sext_i32_i16 s8, s18
	s_addc_u32 s10, s45, s9
	s_lshl_b32 s8, s8, 2
	s_andn2_b32 s8, s8, 63
	s_ashr_i32 s9, s8, 31
	s_lshl_b64 s[8:9], s[8:9], 12
	s_add_u32 s11, s5, s8
	s_addc_u32 s10, s10, s9
	s_ashr_i32 s5, s4, 31
	s_lshl_b64 s[8:9], s[4:5], 2
	s_add_u32 s8, s11, s8
	s_addc_u32 s9, s10, s9
	v_lshl_add_u64 v[0:1], v[34:35], 2, s[8:9]
	v_lshlrev_b32_e32 v188, 2, v32
	v_lshl_add_u64 v[2:3], v[36:37], 2, s[8:9]
	v_lshl_add_u64 v[0:1], v[0:1], 0, v[188:189]
	v_lshl_add_u64 v[2:3], v[2:3], 0, v[188:189]
	global_load_dwordx4 v[4:7], v[0:1], off nt
	s_nop 0
	global_load_dwordx4 v[0:3], v[2:3], off nt
	v_readlane_b32 s41, v252, 41
	v_readlane_b32 s42, v252, 42
	v_readlane_b32 s43, v252, 43
	v_readlane_b32 s46, v252, 46
	v_readlane_b32 s47, v252, 47
	v_readlane_b32 s48, v252, 48
	v_readlane_b32 s49, v252, 49
	v_readlane_b32 s50, v252, 50
	v_readlane_b32 s51, v252, 51
	v_readlane_b32 s52, v252, 52
	v_readlane_b32 s53, v252, 53
	v_readlane_b32 s54, v252, 54
	v_readlane_b32 s55, v252, 55
.LBB0_642:
	s_or_b64 exec, exec, s[6:7]
	s_add_i32 s19, s16, 1
	s_cmpk_lt_i32 s19, 0x200
	s_cselect_b64 s[6:7], -1, 0
	s_cmpk_gt_i32 s19, 0x1ff
	v_mov_b32_e32 v9, 0
	v_mov_b32_e32 v10, 0
	v_mov_b32_e32 v11, 0
	v_mov_b32_e32 v12, 0
	v_mov_b32_e32 v13, 0
	v_mov_b32_e32 v14, 0
	v_mov_b32_e32 v15, 0
	s_cbranch_scc1 .LBB0_646
	s_ashr_i32 s5, s19, 31
	s_lshr_b32 s5, s5, 24
	s_add_i32 s5, s19, s5
	s_and_b32 s8, s5, 0xff00
	s_sub_i32 s8, s19, s8
	s_sext_i32_i16 s9, s8
	s_bfe_u32 s9, s9, 0x4001b
	s_add_i32 s11, s8, s9
	s_and_b32 s9, s11, 0xfff0
	s_sub_i32 s8, s8, s9
	s_sext_i32_i16 s8, s8
	s_lshl_b32 s10, s8, 6
	v_or_b32_e32 v8, s10, v32
	v_cmp_gt_i32_e32 vcc, s93, v8
	v_mov_b32_e32 v15, 0
	v_mov_b32_e32 v14, 0
	v_mov_b32_e32 v13, 0
	v_mov_b32_e32 v12, 0
	v_mov_b32_e32 v11, 0
	v_mov_b32_e32 v10, 0
	v_mov_b32_e32 v9, 0
	v_mov_b32_e32 v8, 0
	s_and_saveexec_b64 s[8:9], vcc
	s_cbranch_execz .LBB0_645
	s_ashr_i32 s12, s5, 8
	s_sext_i32_i16 s11, s11
	s_ashr_i32 s13, s12, 31
	v_readlane_b32 s40, v252, 40
	s_lshr_b32 s11, s11, 4
	s_lshl_b64 s[12:13], s[12:13], 22
	v_readlane_b32 s44, v252, 44
	v_readlane_b32 s45, v252, 45
	s_add_u32 s5, s44, s12
	s_sext_i32_i16 s11, s11
	s_addc_u32 s14, s45, s13
	s_lshl_b32 s12, s11, 6
	s_ashr_i32 s13, s12, 31
	s_lshl_b64 s[12:13], s[12:13], 12
	s_add_u32 s5, s5, s12
	s_addc_u32 s12, s14, s13
	s_ashr_i32 s11, s10, 31
	s_lshl_b64 s[10:11], s[10:11], 2
	s_add_u32 s10, s5, s10
	s_addc_u32 s11, s12, s11
	v_lshl_add_u64 v[8:9], v[34:35], 2, s[10:11]
	v_lshlrev_b32_e32 v188, 2, v32
	v_lshl_add_u64 v[10:11], v[36:37], 2, s[10:11]
	v_lshl_add_u64 v[8:9], v[8:9], 0, v[188:189]
	v_lshl_add_u64 v[10:11], v[10:11], 0, v[188:189]
	global_load_dwordx4 v[12:15], v[8:9], off nt
	s_nop 0
	global_load_dwordx4 v[8:11], v[10:11], off nt
	v_readlane_b32 s41, v252, 41
	v_readlane_b32 s42, v252, 42
	v_readlane_b32 s43, v252, 43
	v_readlane_b32 s46, v252, 46
	v_readlane_b32 s47, v252, 47
	v_readlane_b32 s48, v252, 48
	v_readlane_b32 s49, v252, 49
	v_readlane_b32 s50, v252, 50
	v_readlane_b32 s51, v252, 51
	v_readlane_b32 s52, v252, 52
	v_readlane_b32 s53, v252, 53
	v_readlane_b32 s54, v252, 54
	v_readlane_b32 s55, v252, 55

;     ...
;         for (int q = 0; q < 4; ++q) { const int it = gi * 4 + q;
;             v[q][0] = (f32x4){0.f, 0.f, 0.f, 0.f}; v[q][1] = (f32x4){0.f, 0.f, 0.f, 0.f};
;             if (it < total) { const int b = it / per, r = it % per, k0 = (r / tn) * 64, n0 = (r % tn) * 64;
;                 const float* sp = src + (size_t)b * sbs + (size_t)k0 * N + n0; const int c4 = (tid & 15) * 4;
;                 if (n0 + c4 < N) { v[q][0] = *(const f32x4*)(sp + (size_t)(tid >> 4) * N + c4); v[q][1] = *(const f32x4*)(sp + (size_t)((tid >> 4) + 32) * N + c4); } } }
.LBB0_646:
	s_add_i32 s20, s16, 2
	s_cmpk_lt_i32 s20, 0x200
	v_mov_b32_e32 v16, 0
	s_cselect_b64 s[8:9], -1, 0
	s_cmpk_gt_i32 s20, 0x1ff
	v_mov_b32_e32 v20, 0
	v_mov_b32_e32 v21, 0
	v_mov_b32_e32 v22, 0
	v_mov_b32_e32 v23, 0
	v_mov_b32_e32 v24, 0
	v_mov_b32_e32 v25, 0
	v_mov_b32_e32 v26, 0
	v_mov_b32_e32 v27, 0
	s_cbranch_scc1 .LBB0_650
	s_ashr_i32 s5, s20, 31
	s_lshr_b32 s5, s5, 24
	s_add_i32 s5, s20, s5
	s_and_b32 s10, s5, 0xff00
	s_sub_i32 s10, s20, s10
	s_sext_i32_i16 s11, s10
	s_bfe_u32 s11, s11, 0x4001b
	s_add_i32 s13, s10, s11
	s_and_b32 s11, s13, 0xfff0
	s_sub_i32 s10, s10, s11
	s_sext_i32_i16 s10, s10
	s_lshl_b32 s12, s10, 6
	v_or_b32_e32 v17, s12, v32
	v_cmp_gt_i32_e32 vcc, s93, v17
	v_mov_b32_e32 v27, 0
	v_mov_b32_e32 v26, 0
	v_mov_b32_e32 v25, 0
	v_mov_b32_e32 v24, 0
	v_mov_b32_e32 v23, 0
	v_mov_b32_e32 v22, 0
	v_mov_b32_e32 v21, 0
	v_mov_b32_e32 v20, 0
	s_and_saveexec_b64 s[10:11], vcc
	s_cbranch_execz .LBB0_649
	s_ashr_i32 s14, s5, 8
	s_sext_i32_i16 s13, s13
	s_ashr_i32 s15, s14, 31
	v_readlane_b32 s40, v252, 40
	s_lshr_b32 s13, s13, 4
	s_lshl_b64 s[14:15], s[14:15], 22
	v_readlane_b32 s44, v252, 44
	v_readlane_b32 s45, v252, 45
	s_add_u32 s5, s44, s14
	s_sext_i32_i16 s13, s13
	s_addc_u32 s21, s45, s15
	s_lshl_b32 s14, s13, 6
	s_ashr_i32 s15, s14, 31
	s_lshl_b64 s[14:15], s[14:15], 12
	s_add_u32 s5, s5, s14
	s_addc_u32 s14, s21, s15
	s_ashr_i32 s13, s12, 31
	s_lshl_b64 s[12:13], s[12:13], 2
	s_add_u32 s12, s5, s12
	s_addc_u32 s13, s14, s13
	v_lshl_add_u64 v[18:19], v[34:35], 2, s[12:13]
	v_lshlrev_b32_e32 v188, 2, v32
	v_lshl_add_u64 v[20:21], v[36:37], 2, s[12:13]
	v_lshl_add_u64 v[18:19], v[18:19], 0, v[188:189]
	v_lshl_add_u64 v[20:21], v[20:21], 0, v[188:189]
	global_load_dwordx4 v[24:27], v[18:19], off nt
	s_nop 0
	global_load_dwordx4 v[20:23], v[20:21], off nt
	v_readlane_b32 s41, v252, 41
	v_readlane_b32 s42, v252, 42
	v_readlane_b32 s43, v252, 43
	v_readlane_b32 s46, v252, 46
	v_readlane_b32 s47, v252, 47
	v_readlane_b32 s48, v252, 48
	v_readlane_b32 s49, v252, 49
	v_readlane_b32 s50, v252, 50
	v_readlane_b32 s51, v252, 51
	v_readlane_b32 s52, v252, 52
	v_readlane_b32 s53, v252, 53
	v_readlane_b32 s54, v252, 54
	v_readlane_b32 s55, v252, 55

;     ...
;         for (int q = 0; q < 4; ++q) { const int it = gi * 4 + q;
;             v[q][0] = (f32x4){0.f, 0.f, 0.f, 0.f}; v[q][1] = (f32x4){0.f, 0.f, 0.f, 0.f};
;             if (it < total) { const int b = it / per, r = it % per, k0 = (r / tn) * 64, n0 = (r % tn) * 64;
;                 const float* sp = src + (size_t)b * sbs + (size_t)k0 * N + n0; const int c4 = (tid & 15) * 4;
;                 if (n0 + c4 < N) { v[q][0] = *(const f32x4*)(sp + (size_t)(tid >> 4) * N + c4); v[q][1] = *(const f32x4*)(sp + (size_t)((tid >> 4) + 32) * N + c4); } } }
.LBB0_650:
	s_add_i32 s21, s16, 3
	s_cmpk_lt_i32 s21, 0x200
	s_cselect_b64 s[10:11], -1, 0
	s_cmpk_gt_i32 s21, 0x1ff
	v_mov_b32_e32 v17, 0
	v_mov_b32_e32 v18, 0
	v_mov_b32_e32 v19, 0
	v_mov_b32_e32 v28, 0
	v_mov_b32_e32 v29, 0
	v_mov_b32_e32 v30, 0
	v_mov_b32_e32 v31, 0
	s_cbranch_scc1 .LBB0_654
	s_ashr_i32 s5, s21, 31
	s_lshr_b32 s5, s5, 24
	s_add_i32 s5, s21, s5
	s_and_b32 s12, s5, 0xff00
	s_sub_i32 s12, s21, s12
	s_sext_i32_i16 s13, s12
	s_bfe_u32 s13, s13, 0x4001b
	s_add_i32 s15, s12, s13
	s_and_b32 s13, s15, 0xfff0
	s_sub_i32 s12, s12, s13
	s_sext_i32_i16 s12, s12
	s_lshl_b32 s14, s12, 6
	v_or_b32_e32 v16, s14, v32
	v_cmp_gt_i32_e32 vcc, s93, v16
	v_mov_b32_e32 v31, 0
	v_mov_b32_e32 v30, 0
	v_mov_b32_e32 v29, 0
	v_mov_b32_e32 v28, 0
	v_mov_b32_e32 v19, 0
	v_mov_b32_e32 v18, 0
	v_mov_b32_e32 v17, 0
	v_mov_b32_e32 v16, 0
	s_and_saveexec_b64 s[12:13], vcc
	s_cbranch_execz .LBB0_653
	s_ashr_i32 s22, s5, 8
	s_sext_i32_i16 s15, s15
	s_ashr_i32 s23, s22, 31
	v_readlane_b32 s40, v252, 40
	s_lshr_b32 s15, s15, 4
	s_lshl_b64 s[22:23], s[22:23], 22
	v_readlane_b32 s44, v252, 44
	v_readlane_b32 s45, v252, 45
	s_add_u32 s5, s44, s22
	s_sext_i32_i16 s15, s15
	s_addc_u32 s24, s45, s23
	s_lshl_b32 s22, s15, 6
	s_ashr_i32 s23, s22, 31
	s_lshl_b64 s[22:23], s[22:23], 12
	s_add_u32 s5, s5, s22
	s_addc_u32 s22, s24, s23
	s_ashr_i32 s15, s14, 31
	s_lshl_b64 s[14:15], s[14:15], 2
	s_add_u32 s14, s5, s14
	s_addc_u32 s15, s22, s15
	v_lshl_add_u64 v[16:17], v[34:35], 2, s[14:15]
	v_lshlrev_b32_e32 v188, 2, v32
	v_lshl_add_u64 v[18:19], v[36:37], 2, s[14:15]
	v_lshl_add_u64 v[16:17], v[16:17], 0, v[188:189]
	v_lshl_add_u64 v[18:19], v[18:19], 0, v[188:189]
	global_load_dwordx4 v[28:31], v[16:17], off nt
	s_nop 0
	global_load_dwordx4 v[16:19], v[18:19], off nt
	v_readlane_b32 s41, v252, 41
	v_readlane_b32 s42, v252, 42
	v_readlane_b32 s43, v252, 43
	v_readlane_b32 s46, v252, 46
	v_readlane_b32 s47, v252, 47
	v_readlane_b32 s48, v252, 48
	v_readlane_b32 s49, v252, 49
	v_readlane_b32 s50, v252, 50
	v_readlane_b32 s51, v252, 51
	v_readlane_b32 s52, v252, 52
	v_readlane_b32 s53, v252, 53
	v_readlane_b32 s54, v252, 54
	v_readlane_b32 s55, v252, 55
